# D*x skip term folded into the forward march's y rows (f32, before the single bf16 rounding); the combine pass reads one stream less
# speedup vs baseline: 1.0057x; 1.0057x over previous
.LBB0_236:
	s_mov_b32 s87, s12
	s_lshl_b64 s[4:5], s[86:87], 4
	s_add_u32 s4, s60, s4
	s_addc_u32 s5, s61, s5
	s_load_dwordx4 s[96:99], s[4:5], 0xc0
	s_mov_b64 s[4:5], -1
	s_waitcnt lgkmcnt(0)
	s_ashr_i32 s42, s97, 1
	s_cmp_lt_i32 s96, 3
	s_cbranch_scc1 .LBB0_327
	s_cmp_lt_i32 s96, 4
	s_cbranch_scc1 .LBB0_311
	s_cmp_lt_i32 s96, 5
	s_cbranch_scc1 .LBB0_245
	s_cmp_eq_u32 s96, 5
	s_cbranch_scc0 .LBB0_244
	v_lshrrev_b32_e32 v1, 6, v175
	v_readlane_b32 s3, v253, 4
	v_readfirstlane_b32 s43, v1
	s_nop 3
	s_add_u32 s18, s3, s43
	v_readlane_b32 s4, v254, 18
	v_readlane_b32 s5, v254, 19
	v_readlane_b32 s6, v254, 16
	v_readlane_b32 s7, v254, 17
	s_lshl_b32 s8, s42, 13
	s_add_u32 s4, s4, s8
	s_addc_u32 s5, s5, 0
	s_lshl_b32 s8, s42, 7
	s_add_u32 s6, s6, s8
	s_addc_u32 s7, s7, 0
	v_and_b32_e32 v2, 31, v175
	v_bfe_u32 v3, v175, 5, 1
	s_lshl_b32 s8, s18, 1
	s_and_b32 s8, s8, 6
	v_or_b32_e32 v3, s8, v3
	v_lshlrev_b32_e32 v46, 3, v2
	v_lshl_or_b32 v46, v3, 8, v46
	v_lshlrev_b32_e32 v100, 1, v46
	v_lshrrev_b32_e32 v47, 5, v46
	v_and_b32_e32 v48, 3, v2
	v_lshlrev_b32_e32 v48, 4, v48
	v_lshl_or_b32 v101, v47, 20, v48
	v_lshlrev_b32_e32 v47, 2, v46
	global_load_dwordx4 v[36:39], v47, s[4:5]
	global_load_dwordx4 v[40:43], v47, s[4:5] offset:16
	v_lshrrev_b32_e32 v48, 3, v2
	v_lshl_or_b32 v48, v3, 2, v48
	v_lshlrev_b32_e32 v48, 2, v48
	global_load_dword v44, v48, s[6:7]
	s_lshr_b32 s43, s18, 2
	s_lshl_b32 s3, s43, 12
	s_add_u32 s4, s48, s3
	s_addc_u32 s5, s49, 0
	s_add_u32 s6, s52, s3
	s_addc_u32 s7, s53, 0
	s_add_u32 s8, s50, s3
	s_addc_u32 s9, s51, 0
	s_lshl_b32 s3, s43, 6
	s_add_u32 s14, s46, s3
	s_addc_u32 s15, s47, 0
	s_lshl_b32 s16, s28, 10
	s_lshl_b32 s17, s28, 4
	s_mov_b32 vcc_lo, s8
	s_mov_b32 vcc_hi, s9
	global_load_dwordx4 v[4:7], v100, s[4:5] nt
	global_load_dwordx4 v[8:11], v100, s[6:7] nt
	global_load_dwordx4 v[12:15], v100, vcc
	s_add_u32 s4, s4, s16
	s_addc_u32 s5, s5, 0
	s_add_u32 s6, s6, s16
	s_addc_u32 s7, s7, 0
	s_add_u32 vcc_lo, vcc_lo, s16
	s_addc_u32 vcc_hi, vcc_hi, 0
	global_load_dwordx4 v[20:23], v100, s[4:5] nt
	global_load_dwordx4 v[24:27], v100, s[6:7] nt
	global_load_dwordx4 v[28:31], v100, vcc
	s_add_u32 s4, s4, s16
	s_addc_u32 s5, s5, 0
	s_add_u32 s6, s6, s16
	s_addc_u32 s7, s7, 0
	s_add_u32 vcc_lo, vcc_lo, s16
	s_addc_u32 vcc_hi, vcc_hi, 0
	s_waitcnt vmcnt(3)
	v_lshlrev_b32_e32 v46, 16, v12
	v_and_b32_e32 v47, 0xffff0000, v12
	v_lshlrev_b32_e32 v48, 16, v13
	v_and_b32_e32 v49, 0xffff0000, v13
	v_lshlrev_b32_e32 v50, 16, v14
	v_and_b32_e32 v51, 0xffff0000, v14
	v_lshlrev_b32_e32 v52, 16, v15
	v_and_b32_e32 v53, 0xffff0000, v15
	v_mul_f32_e32 v54, 0xbfb8aa3b, v46
	v_mul_f32_e32 v55, 0xbfb8aa3b, v47
	v_mul_f32_e32 v56, 0xbfb8aa3b, v48
	v_mul_f32_e32 v57, 0xbfb8aa3b, v49
	v_mul_f32_e32 v58, 0xbfb8aa3b, v50
	v_mul_f32_e32 v59, 0xbfb8aa3b, v51
	v_mul_f32_e32 v60, 0xbfb8aa3b, v52
	v_mul_f32_e32 v61, 0xbfb8aa3b, v53
	v_exp_f32_e32 v54, v54
	v_exp_f32_e32 v55, v55
	v_exp_f32_e32 v56, v56
	v_exp_f32_e32 v57, v57
	v_exp_f32_e32 v58, v58
	v_exp_f32_e32 v59, v59
	v_exp_f32_e32 v60, v60
	v_exp_f32_e32 v61, v61
	v_lshlrev_b32_e32 v62, 16, v4
	v_and_b32_e32 v63, 0xffff0000, v4
	v_lshlrev_b32_e32 v78, 16, v8
	v_and_b32_e32 v79, 0xffff0000, v8
	v_lshlrev_b32_e32 v64, 16, v5
	v_and_b32_e32 v65, 0xffff0000, v5
	v_lshlrev_b32_e32 v80, 16, v9
	v_and_b32_e32 v81, 0xffff0000, v9
	v_lshlrev_b32_e32 v66, 16, v6
	v_and_b32_e32 v67, 0xffff0000, v6
	v_lshlrev_b32_e32 v82, 16, v10
	v_and_b32_e32 v83, 0xffff0000, v10
	v_lshlrev_b32_e32 v68, 16, v7
	v_and_b32_e32 v69, 0xffff0000, v7
	v_lshlrev_b32_e32 v84, 16, v11
	v_and_b32_e32 v85, 0xffff0000, v11
	v_add_f32_e32 v54, 1.0, v54
	v_add_f32_e32 v55, 1.0, v55
	v_add_f32_e32 v56, 1.0, v56
	v_add_f32_e32 v57, 1.0, v57
	v_add_f32_e32 v58, 1.0, v58
	v_add_f32_e32 v59, 1.0, v59
	v_add_f32_e32 v60, 1.0, v60
	v_add_f32_e32 v61, 1.0, v61
	v_rcp_f32_e32 v54, v54
	v_rcp_f32_e32 v55, v55
	v_rcp_f32_e32 v56, v56
	v_rcp_f32_e32 v57, v57
	v_rcp_f32_e32 v58, v58
	v_rcp_f32_e32 v59, v59
	v_rcp_f32_e32 v60, v60
	v_rcp_f32_e32 v61, v61
	v_pk_add_f32 v[62:63], v[62:63], v[78:79]
	v_pk_add_f32 v[64:65], v[64:65], v[80:81]
	v_pk_add_f32 v[66:67], v[66:67], v[82:83]
	v_pk_add_f32 v[68:69], v[68:69], v[84:85]
	v_pk_mul_f32 v[54:55], v[54:55], v[46:47]
	v_pk_mul_f32 v[56:57], v[56:57], v[48:49]
	v_pk_mul_f32 v[58:59], v[58:59], v[50:51]
	v_pk_mul_f32 v[60:61], v[60:61], v[52:53]
	v_pk_mul_f32 v[62:63], v[62:63], v[54:55]
	v_pk_mul_f32 v[64:65], v[64:65], v[56:57]
	v_pk_mul_f32 v[66:67], v[66:67], v[58:59]
	v_pk_mul_f32 v[68:69], v[68:69], v[60:61]
	v_pk_mul_f32 v[46:47], v[62:63], v[62:63]
	v_pk_mul_f32 v[48:49], v[66:67], v[66:67]
	v_pk_fma_f32 v[46:47], v[64:65], v[64:65], v[46:47]
	v_pk_fma_f32 v[48:49], v[68:69], v[68:69], v[48:49]
	v_pk_add_f32 v[46:47], v[46:47], v[48:49]
	s_nop 0
	v_add_f32_e32 v46, v46, v47
	s_nop 1
	v_add_f32_dpp v46, v46, v46 quad_perm:[1,0,3,2] row_mask:0xf bank_mask:0xf
	s_nop 1
	v_add_f32_dpp v46, v46, v46 quad_perm:[2,3,0,1] row_mask:0xf bank_mask:0xf
	s_nop 1
	v_add_f32_dpp v46, v46, v46 row_half_mirror row_mask:0xf bank_mask:0xf
	s_nop 1
	v_add_f32_dpp v46, v46, v46 row_mirror row_mask:0xf bank_mask:0xf
	s_nop 1
	ds_swizzle_b32 v47, v46 offset:swizzle(SWAP,16)
	s_waitcnt lgkmcnt(0)
	v_add_f32_e32 v46, v46, v47
	v_fmamk_f32 v46, v46, 0x3b800000, v174
	v_rsq_f32_e32 v46, v46
	s_nop 0
	v_pk_mul_f32 v[62:63], v[62:63], v[46:47] op_sel_hi:[1,0]
	v_pk_mul_f32 v[64:65], v[64:65], v[46:47] op_sel_hi:[1,0]
	v_pk_mul_f32 v[66:67], v[66:67], v[46:47] op_sel_hi:[1,0]
	v_pk_mul_f32 v[68:69], v[68:69], v[46:47] op_sel_hi:[1,0]
	v_pk_mul_f32 v[62:63], v[62:63], v[36:37]
	v_pk_mul_f32 v[64:65], v[64:65], v[38:39]
	v_pk_mul_f32 v[66:67], v[66:67], v[40:41]
	v_pk_mul_f32 v[68:69], v[68:69], v[42:43]
	v_cvt_pk_bf16_f32 v88, v62, v63
	v_cvt_pk_bf16_f32 v89, v64, v65
	v_cvt_pk_bf16_f32 v90, v66, v67
	v_cvt_pk_bf16_f32 v91, v68, v69
	global_load_dwordx4 v[4:7], v100, s[4:5] nt
	global_load_dwordx4 v[8:11], v100, s[6:7] nt
	global_load_dwordx4 v[12:15], v100, vcc
	s_add_u32 s4, s4, s16
	s_addc_u32 s5, s5, 0
	s_add_u32 s6, s6, s16
	s_addc_u32 s7, s7, 0
	s_add_u32 vcc_lo, vcc_lo, s16
	s_addc_u32 vcc_hi, vcc_hi, 0
	global_store_dwordx4 v100, v[88:91], s[8:9]
	s_add_u32 s8, s8, s16
	s_addc_u32 s9, s9, 0
	s_add_u32 s18, s18, s28
	s_cmp_lt_u32 s18, s35
	s_cbranch_scc0 .Lc_exit
	s_waitcnt vmcnt(4)
	v_lshlrev_b32_e32 v46, 16, v28
	v_and_b32_e32 v47, 0xffff0000, v28
	v_lshlrev_b32_e32 v48, 16, v29
	v_and_b32_e32 v49, 0xffff0000, v29
	v_lshlrev_b32_e32 v50, 16, v30
	v_and_b32_e32 v51, 0xffff0000, v30
	v_lshlrev_b32_e32 v52, 16, v31
	v_and_b32_e32 v53, 0xffff0000, v31
	v_mul_f32_e32 v54, 0xbfb8aa3b, v46
	v_mul_f32_e32 v55, 0xbfb8aa3b, v47
	v_mul_f32_e32 v56, 0xbfb8aa3b, v48
	v_mul_f32_e32 v57, 0xbfb8aa3b, v49
	v_mul_f32_e32 v58, 0xbfb8aa3b, v50
	v_mul_f32_e32 v59, 0xbfb8aa3b, v51
	v_mul_f32_e32 v60, 0xbfb8aa3b, v52
	v_mul_f32_e32 v61, 0xbfb8aa3b, v53
	v_exp_f32_e32 v54, v54
	v_exp_f32_e32 v55, v55
	v_exp_f32_e32 v56, v56
	v_exp_f32_e32 v57, v57
	v_exp_f32_e32 v58, v58
	v_exp_f32_e32 v59, v59
	v_exp_f32_e32 v60, v60
	v_exp_f32_e32 v61, v61
	v_lshlrev_b32_e32 v62, 16, v20
	v_and_b32_e32 v63, 0xffff0000, v20
	v_lshlrev_b32_e32 v78, 16, v24
	v_and_b32_e32 v79, 0xffff0000, v24
	v_lshlrev_b32_e32 v64, 16, v21
	v_and_b32_e32 v65, 0xffff0000, v21
	v_lshlrev_b32_e32 v80, 16, v25
	v_and_b32_e32 v81, 0xffff0000, v25
	v_lshlrev_b32_e32 v66, 16, v22
	v_and_b32_e32 v67, 0xffff0000, v22
	v_lshlrev_b32_e32 v82, 16, v26
	v_and_b32_e32 v83, 0xffff0000, v26
	v_lshlrev_b32_e32 v68, 16, v23
	v_and_b32_e32 v69, 0xffff0000, v23
	v_lshlrev_b32_e32 v84, 16, v27
	v_and_b32_e32 v85, 0xffff0000, v27
	v_add_f32_e32 v54, 1.0, v54
	v_add_f32_e32 v55, 1.0, v55
	v_add_f32_e32 v56, 1.0, v56
	v_add_f32_e32 v57, 1.0, v57
	v_add_f32_e32 v58, 1.0, v58
	v_add_f32_e32 v59, 1.0, v59
	v_add_f32_e32 v60, 1.0, v60
	v_add_f32_e32 v61, 1.0, v61
	v_rcp_f32_e32 v54, v54
	v_rcp_f32_e32 v55, v55
	v_rcp_f32_e32 v56, v56
	v_rcp_f32_e32 v57, v57
	v_rcp_f32_e32 v58, v58
	v_rcp_f32_e32 v59, v59
	v_rcp_f32_e32 v60, v60
	v_rcp_f32_e32 v61, v61
	v_pk_add_f32 v[62:63], v[62:63], v[78:79]
	v_pk_add_f32 v[64:65], v[64:65], v[80:81]
	v_pk_add_f32 v[66:67], v[66:67], v[82:83]
	v_pk_add_f32 v[68:69], v[68:69], v[84:85]
	v_pk_mul_f32 v[54:55], v[54:55], v[46:47]
	v_pk_mul_f32 v[56:57], v[56:57], v[48:49]
	v_pk_mul_f32 v[58:59], v[58:59], v[50:51]
	v_pk_mul_f32 v[60:61], v[60:61], v[52:53]
	v_pk_mul_f32 v[62:63], v[62:63], v[54:55]
	v_pk_mul_f32 v[64:65], v[64:65], v[56:57]
	v_pk_mul_f32 v[66:67], v[66:67], v[58:59]
	v_pk_mul_f32 v[68:69], v[68:69], v[60:61]
	v_pk_mul_f32 v[46:47], v[62:63], v[62:63]
	v_pk_mul_f32 v[48:49], v[66:67], v[66:67]
	v_pk_fma_f32 v[46:47], v[64:65], v[64:65], v[46:47]
	v_pk_fma_f32 v[48:49], v[68:69], v[68:69], v[48:49]
	v_pk_add_f32 v[46:47], v[46:47], v[48:49]
	s_nop 0
	v_add_f32_e32 v46, v46, v47
	s_nop 1
	v_add_f32_dpp v46, v46, v46 quad_perm:[1,0,3,2] row_mask:0xf bank_mask:0xf
	s_nop 1
	v_add_f32_dpp v46, v46, v46 quad_perm:[2,3,0,1] row_mask:0xf bank_mask:0xf
	s_nop 1
	v_add_f32_dpp v46, v46, v46 row_half_mirror row_mask:0xf bank_mask:0xf
	s_nop 1
	v_add_f32_dpp v46, v46, v46 row_mirror row_mask:0xf bank_mask:0xf
	s_nop 1
	ds_swizzle_b32 v47, v46 offset:swizzle(SWAP,16)
	s_waitcnt lgkmcnt(0)
	v_add_f32_e32 v46, v46, v47
	v_fmamk_f32 v46, v46, 0x3b800000, v174
	v_rsq_f32_e32 v46, v46
	s_nop 0
	v_pk_mul_f32 v[62:63], v[62:63], v[46:47] op_sel_hi:[1,0]
	v_pk_mul_f32 v[64:65], v[64:65], v[46:47] op_sel_hi:[1,0]
	v_pk_mul_f32 v[66:67], v[66:67], v[46:47] op_sel_hi:[1,0]
	v_pk_mul_f32 v[68:69], v[68:69], v[46:47] op_sel_hi:[1,0]
	v_pk_mul_f32 v[62:63], v[62:63], v[36:37]
	v_pk_mul_f32 v[64:65], v[64:65], v[38:39]
	v_pk_mul_f32 v[66:67], v[66:67], v[40:41]
	v_pk_mul_f32 v[68:69], v[68:69], v[42:43]
	v_cvt_pk_bf16_f32 v88, v62, v63
	v_cvt_pk_bf16_f32 v89, v64, v65
	v_cvt_pk_bf16_f32 v90, v66, v67
	v_cvt_pk_bf16_f32 v91, v68, v69
	global_load_dwordx4 v[20:23], v100, s[4:5] nt
	global_load_dwordx4 v[24:27], v100, s[6:7] nt
	global_load_dwordx4 v[28:31], v100, vcc
	s_add_u32 s4, s4, s16
	s_addc_u32 s5, s5, 0
	s_add_u32 s6, s6, s16
	s_addc_u32 s7, s7, 0
	s_add_u32 vcc_lo, vcc_lo, s16
	s_addc_u32 vcc_hi, vcc_hi, 0
	global_store_dwordx4 v100, v[88:91], s[8:9]
	s_add_u32 s8, s8, s16
	s_addc_u32 s9, s9, 0
	s_add_u32 s18, s18, s28
	s_cmp_lt_u32 s18, s35
	s_cbranch_scc0 .Lc_exit
.Lc_loop:
	s_waitcnt vmcnt(5)
	v_lshlrev_b32_e32 v46, 16, v12
	v_and_b32_e32 v47, 0xffff0000, v12
	v_lshlrev_b32_e32 v48, 16, v13
	v_and_b32_e32 v49, 0xffff0000, v13
	v_lshlrev_b32_e32 v50, 16, v14
	v_and_b32_e32 v51, 0xffff0000, v14
	v_lshlrev_b32_e32 v52, 16, v15
	v_and_b32_e32 v53, 0xffff0000, v15
	v_mul_f32_e32 v54, 0xbfb8aa3b, v46
	v_mul_f32_e32 v55, 0xbfb8aa3b, v47
	v_mul_f32_e32 v56, 0xbfb8aa3b, v48
	v_mul_f32_e32 v57, 0xbfb8aa3b, v49
	v_mul_f32_e32 v58, 0xbfb8aa3b, v50
	v_mul_f32_e32 v59, 0xbfb8aa3b, v51
	v_mul_f32_e32 v60, 0xbfb8aa3b, v52
	v_mul_f32_e32 v61, 0xbfb8aa3b, v53
	v_exp_f32_e32 v54, v54
	v_exp_f32_e32 v55, v55
	v_exp_f32_e32 v56, v56
	v_exp_f32_e32 v57, v57
	v_exp_f32_e32 v58, v58
	v_exp_f32_e32 v59, v59
	v_exp_f32_e32 v60, v60
	v_exp_f32_e32 v61, v61
	v_lshlrev_b32_e32 v62, 16, v4
	v_and_b32_e32 v63, 0xffff0000, v4
	v_lshlrev_b32_e32 v78, 16, v8
	v_and_b32_e32 v79, 0xffff0000, v8
	v_lshlrev_b32_e32 v64, 16, v5
	v_and_b32_e32 v65, 0xffff0000, v5
	v_lshlrev_b32_e32 v80, 16, v9
	v_and_b32_e32 v81, 0xffff0000, v9
	v_lshlrev_b32_e32 v66, 16, v6
	v_and_b32_e32 v67, 0xffff0000, v6
	v_lshlrev_b32_e32 v82, 16, v10
	v_and_b32_e32 v83, 0xffff0000, v10
	v_lshlrev_b32_e32 v68, 16, v7
	v_and_b32_e32 v69, 0xffff0000, v7
	v_lshlrev_b32_e32 v84, 16, v11
	v_and_b32_e32 v85, 0xffff0000, v11
	v_add_f32_e32 v54, 1.0, v54
	v_add_f32_e32 v55, 1.0, v55
	v_add_f32_e32 v56, 1.0, v56
	v_add_f32_e32 v57, 1.0, v57
	v_add_f32_e32 v58, 1.0, v58
	v_add_f32_e32 v59, 1.0, v59
	v_add_f32_e32 v60, 1.0, v60
	v_add_f32_e32 v61, 1.0, v61
	v_rcp_f32_e32 v54, v54
	v_rcp_f32_e32 v55, v55
	v_rcp_f32_e32 v56, v56
	v_rcp_f32_e32 v57, v57
	v_rcp_f32_e32 v58, v58
	v_rcp_f32_e32 v59, v59
	v_rcp_f32_e32 v60, v60
	v_rcp_f32_e32 v61, v61
	v_pk_add_f32 v[62:63], v[62:63], v[78:79]
	v_pk_add_f32 v[64:65], v[64:65], v[80:81]
	v_pk_add_f32 v[66:67], v[66:67], v[82:83]
	v_pk_add_f32 v[68:69], v[68:69], v[84:85]
	v_pk_mul_f32 v[54:55], v[54:55], v[46:47]
	v_pk_mul_f32 v[56:57], v[56:57], v[48:49]
	v_pk_mul_f32 v[58:59], v[58:59], v[50:51]
	v_pk_mul_f32 v[60:61], v[60:61], v[52:53]
	v_pk_mul_f32 v[62:63], v[62:63], v[54:55]
	v_pk_mul_f32 v[64:65], v[64:65], v[56:57]
	v_pk_mul_f32 v[66:67], v[66:67], v[58:59]
	v_pk_mul_f32 v[68:69], v[68:69], v[60:61]
	v_pk_mul_f32 v[46:47], v[62:63], v[62:63]
	v_pk_mul_f32 v[48:49], v[66:67], v[66:67]
	v_pk_fma_f32 v[46:47], v[64:65], v[64:65], v[46:47]
	v_pk_fma_f32 v[48:49], v[68:69], v[68:69], v[48:49]
	v_pk_add_f32 v[46:47], v[46:47], v[48:49]
	s_nop 0
	v_add_f32_e32 v46, v46, v47
	s_nop 1
	v_add_f32_dpp v46, v46, v46 quad_perm:[1,0,3,2] row_mask:0xf bank_mask:0xf
	s_nop 1
	v_add_f32_dpp v46, v46, v46 quad_perm:[2,3,0,1] row_mask:0xf bank_mask:0xf
	s_nop 1
	v_add_f32_dpp v46, v46, v46 row_half_mirror row_mask:0xf bank_mask:0xf
	s_nop 1
	v_add_f32_dpp v46, v46, v46 row_mirror row_mask:0xf bank_mask:0xf
	s_nop 1
	ds_swizzle_b32 v47, v46 offset:swizzle(SWAP,16)
	s_waitcnt lgkmcnt(0)
	v_add_f32_e32 v46, v46, v47
	v_fmamk_f32 v46, v46, 0x3b800000, v174
	v_rsq_f32_e32 v46, v46
	s_nop 0
	v_pk_mul_f32 v[62:63], v[62:63], v[46:47] op_sel_hi:[1,0]
	v_pk_mul_f32 v[64:65], v[64:65], v[46:47] op_sel_hi:[1,0]
	v_pk_mul_f32 v[66:67], v[66:67], v[46:47] op_sel_hi:[1,0]
	v_pk_mul_f32 v[68:69], v[68:69], v[46:47] op_sel_hi:[1,0]
	v_pk_mul_f32 v[62:63], v[62:63], v[36:37]
	v_pk_mul_f32 v[64:65], v[64:65], v[38:39]
	v_pk_mul_f32 v[66:67], v[66:67], v[40:41]
	v_pk_mul_f32 v[68:69], v[68:69], v[42:43]
	v_cvt_pk_bf16_f32 v88, v62, v63
	v_cvt_pk_bf16_f32 v89, v64, v65
	v_cvt_pk_bf16_f32 v90, v66, v67
	v_cvt_pk_bf16_f32 v91, v68, v69
	global_load_dwordx4 v[4:7], v100, s[4:5] nt
	global_load_dwordx4 v[8:11], v100, s[6:7] nt
	global_load_dwordx4 v[12:15], v100, vcc
	s_add_u32 s4, s4, s16
	s_addc_u32 s5, s5, 0
	s_add_u32 s6, s6, s16
	s_addc_u32 s7, s7, 0
	s_add_u32 vcc_lo, vcc_lo, s16
	s_addc_u32 vcc_hi, vcc_hi, 0
	global_store_dwordx4 v100, v[88:91], s[8:9]
	s_add_u32 s8, s8, s16
	s_addc_u32 s9, s9, 0
	s_add_u32 s18, s18, s28
	s_cmp_lt_u32 s18, s35
	s_cbranch_scc0 .Lc_exit
	s_waitcnt vmcnt(5)
	v_lshlrev_b32_e32 v46, 16, v28
	v_and_b32_e32 v47, 0xffff0000, v28
	v_lshlrev_b32_e32 v48, 16, v29
	v_and_b32_e32 v49, 0xffff0000, v29
	v_lshlrev_b32_e32 v50, 16, v30
	v_and_b32_e32 v51, 0xffff0000, v30
	v_lshlrev_b32_e32 v52, 16, v31
	v_and_b32_e32 v53, 0xffff0000, v31
	v_mul_f32_e32 v54, 0xbfb8aa3b, v46
	v_mul_f32_e32 v55, 0xbfb8aa3b, v47
	v_mul_f32_e32 v56, 0xbfb8aa3b, v48
	v_mul_f32_e32 v57, 0xbfb8aa3b, v49
	v_mul_f32_e32 v58, 0xbfb8aa3b, v50
	v_mul_f32_e32 v59, 0xbfb8aa3b, v51
	v_mul_f32_e32 v60, 0xbfb8aa3b, v52
	v_mul_f32_e32 v61, 0xbfb8aa3b, v53
	v_exp_f32_e32 v54, v54
	v_exp_f32_e32 v55, v55
	v_exp_f32_e32 v56, v56
	v_exp_f32_e32 v57, v57
	v_exp_f32_e32 v58, v58
	v_exp_f32_e32 v59, v59
	v_exp_f32_e32 v60, v60
	v_exp_f32_e32 v61, v61
	v_lshlrev_b32_e32 v62, 16, v20
	v_and_b32_e32 v63, 0xffff0000, v20
	v_lshlrev_b32_e32 v78, 16, v24
	v_and_b32_e32 v79, 0xffff0000, v24
	v_lshlrev_b32_e32 v64, 16, v21
	v_and_b32_e32 v65, 0xffff0000, v21
	v_lshlrev_b32_e32 v80, 16, v25
	v_and_b32_e32 v81, 0xffff0000, v25
	v_lshlrev_b32_e32 v66, 16, v22
	v_and_b32_e32 v67, 0xffff0000, v22
	v_lshlrev_b32_e32 v82, 16, v26
	v_and_b32_e32 v83, 0xffff0000, v26
	v_lshlrev_b32_e32 v68, 16, v23
	v_and_b32_e32 v69, 0xffff0000, v23
	v_lshlrev_b32_e32 v84, 16, v27
	v_and_b32_e32 v85, 0xffff0000, v27
	v_add_f32_e32 v54, 1.0, v54
	v_add_f32_e32 v55, 1.0, v55
	v_add_f32_e32 v56, 1.0, v56
	v_add_f32_e32 v57, 1.0, v57
	v_add_f32_e32 v58, 1.0, v58
	v_add_f32_e32 v59, 1.0, v59
	v_add_f32_e32 v60, 1.0, v60
	v_add_f32_e32 v61, 1.0, v61
	v_rcp_f32_e32 v54, v54
	v_rcp_f32_e32 v55, v55
	v_rcp_f32_e32 v56, v56
	v_rcp_f32_e32 v57, v57
	v_rcp_f32_e32 v58, v58
	v_rcp_f32_e32 v59, v59
	v_rcp_f32_e32 v60, v60
	v_rcp_f32_e32 v61, v61
	v_pk_add_f32 v[62:63], v[62:63], v[78:79]
	v_pk_add_f32 v[64:65], v[64:65], v[80:81]
	v_pk_add_f32 v[66:67], v[66:67], v[82:83]
	v_pk_add_f32 v[68:69], v[68:69], v[84:85]
	v_pk_mul_f32 v[54:55], v[54:55], v[46:47]
	v_pk_mul_f32 v[56:57], v[56:57], v[48:49]
	v_pk_mul_f32 v[58:59], v[58:59], v[50:51]
	v_pk_mul_f32 v[60:61], v[60:61], v[52:53]
	v_pk_mul_f32 v[62:63], v[62:63], v[54:55]
	v_pk_mul_f32 v[64:65], v[64:65], v[56:57]
	v_pk_mul_f32 v[66:67], v[66:67], v[58:59]
	v_pk_mul_f32 v[68:69], v[68:69], v[60:61]
	v_pk_mul_f32 v[46:47], v[62:63], v[62:63]
	v_pk_mul_f32 v[48:49], v[66:67], v[66:67]
	v_pk_fma_f32 v[46:47], v[64:65], v[64:65], v[46:47]
	v_pk_fma_f32 v[48:49], v[68:69], v[68:69], v[48:49]
	v_pk_add_f32 v[46:47], v[46:47], v[48:49]
	s_nop 0
	v_add_f32_e32 v46, v46, v47
	s_nop 1
	v_add_f32_dpp v46, v46, v46 quad_perm:[1,0,3,2] row_mask:0xf bank_mask:0xf
	s_nop 1
	v_add_f32_dpp v46, v46, v46 quad_perm:[2,3,0,1] row_mask:0xf bank_mask:0xf
	s_nop 1
	v_add_f32_dpp v46, v46, v46 row_half_mirror row_mask:0xf bank_mask:0xf
	s_nop 1
	v_add_f32_dpp v46, v46, v46 row_mirror row_mask:0xf bank_mask:0xf
	s_nop 1
	ds_swizzle_b32 v47, v46 offset:swizzle(SWAP,16)
	s_waitcnt lgkmcnt(0)
	v_add_f32_e32 v46, v46, v47
	v_fmamk_f32 v46, v46, 0x3b800000, v174
	v_rsq_f32_e32 v46, v46
	s_nop 0
	v_pk_mul_f32 v[62:63], v[62:63], v[46:47] op_sel_hi:[1,0]
	v_pk_mul_f32 v[64:65], v[64:65], v[46:47] op_sel_hi:[1,0]
	v_pk_mul_f32 v[66:67], v[66:67], v[46:47] op_sel_hi:[1,0]
	v_pk_mul_f32 v[68:69], v[68:69], v[46:47] op_sel_hi:[1,0]
	v_pk_mul_f32 v[62:63], v[62:63], v[36:37]
	v_pk_mul_f32 v[64:65], v[64:65], v[38:39]
	v_pk_mul_f32 v[66:67], v[66:67], v[40:41]
	v_pk_mul_f32 v[68:69], v[68:69], v[42:43]
	v_cvt_pk_bf16_f32 v88, v62, v63
	v_cvt_pk_bf16_f32 v89, v64, v65
	v_cvt_pk_bf16_f32 v90, v66, v67
	v_cvt_pk_bf16_f32 v91, v68, v69
	global_load_dwordx4 v[20:23], v100, s[4:5] nt
	global_load_dwordx4 v[24:27], v100, s[6:7] nt
	global_load_dwordx4 v[28:31], v100, vcc
	s_add_u32 s4, s4, s16
	s_addc_u32 s5, s5, 0
	s_add_u32 s6, s6, s16
	s_addc_u32 s7, s7, 0
	s_add_u32 vcc_lo, vcc_lo, s16
	s_addc_u32 vcc_hi, vcc_hi, 0
	global_store_dwordx4 v100, v[88:91], s[8:9]
	s_add_u32 s8, s8, s16
	s_addc_u32 s9, s9, 0
	s_add_u32 s18, s18, s28
	s_cmp_lt_u32 s18, s35
	s_cbranch_scc0 .Lc_exit
	s_branch .Lc_loop

.LBB0_245:
	s_andn2_b64 vcc, exec, s[4:5]
	s_cbranch_vccnz .LBB0_310
	v_readlane_b32 s4, v253, 14
	v_mov_b32_e32 v1, v175
	v_readlane_b32 s5, v253, 15
	s_andn2_b64 vcc, exec, s[4:5]
	v_readfirstlane_b32 s3, v1
	s_cbranch_vccnz .LBB0_310
	v_writelane_b32 v255, s96, 7
	v_writelane_b32 v255, s97, 8
	v_writelane_b32 v255, s98, 9
	v_writelane_b32 v255, s99, 10
	v_writelane_b32 v255, s86, 0
	v_writelane_b32 v255, s87, 1
	v_writelane_b32 v255, s42, 11
	v_writelane_b32 v255, s43, 12
	v_lshrrev_b32_e32 v1, 6, v175
	s_lshl_b32 s4, s42, 8
	v_readfirstlane_b32 s3, v1
	s_add_u32 s56, s94, s4
	s_addc_u32 s57, s95, 0
	v_readlane_b32 s58, v253, 3
	v_readlane_b32 s61, v253, 5
	v_readlane_b32 s22, v254, 16
	v_readlane_b32 s23, v254, 17
	s_lshl_b32 s25, s42, 7
	s_movk_i32 s59, 0x110
	s_movk_i32 s60, 0x40
	s_nop 3
.Lm_item:
	s_barrier
	s_and_b32 s4, s61, 7
	s_lshr_b32 s5, s61, 3
	s_lshr_b32 s6, s5, 3
	s_lshl_b32 s4, s4, 2
	s_add_u32 s4, s4, s6
	s_and_b32 s5, s5, 7
	s_lshr_b32 s6, s4, 4
	s_bfe_u32 s7, s4, 0x30001
	s_and_b32 s51, s4, 1
	s_lshr_b32 s8, s5, 1
	s_lshl_b32 s9, s7, 2
	s_add_u32 s8, s9, s8
	s_and_b32 s5, s5, 1
	s_lshl_b32 s9, s51, 5
	s_add_u32 s9, s9, s8
	s_lshl_b32 s9, s9, 2
	s_load_dword s10, s[56:57], s9
	s_lshl_b32 s15, s8, 2
	s_add_u32 s15, s15, s25
	s_waitcnt lgkmcnt(0)
	s_load_dword s24, s[22:23], s15
	s_mov_b32 s55, 0
	s_mov_b32 s46, 0x10000
	s_mov_b32 s47, 0x2000
	s_mov_b32 s48, 0x8000
	s_mov_b32 s49, 0x80000
	s_mov_b32 s11, 0
	s_cmp_eq_u32 s51, 0
	s_cbranch_scc1 .Lm_fwd_1
	s_mov_b32 s55, -1
	s_sub_u32 s46, 0, s46
	s_sub_u32 s47, 0, s47
	s_sub_u32 s48, 0, s48
	s_sub_u32 s49, 0, s49
	s_mov_b32 s11, 63
.Lm_fwd_1:
	s_lshl_b32 s15, s7, 23
	s_lshl_b32 s96, s6, 22
	s_add_u32 s15, s15, s96
	s_lshl_b32 s96, s11, 16
	s_add_u32 s15, s15, s96
	s_add_u32 s15, s15, 0x1b000000
	s_add_u32 s38, s36, s15
	s_addc_u32 s39, s37, 0
	s_lshl_b32 s15, s8, 1
	s_add_u32 s15, s15, s5
	s_lshl_b32 s15, s15, 20
	s_lshl_b32 s96, s6, 19
	s_add_u32 s15, s15, s96
	s_lshl_b32 s96, s11, 13
	s_add_u32 s15, s15, s96
	s_add_u32 s15, s15, 0x17000000
	s_add_u32 s40, s36, s15
	s_addc_u32 s41, s37, 0
	s_lshl_b32 s15, s6, 21
	s_add_u32 s15, s15, s9
	s_lshl_b32 s96, s11, 15
	s_add_u32 s15, s15, s96
	s_add_u32 s15, s15, 0x1f000000
	s_add_u32 s42, s36, s15
	s_addc_u32 s43, s37, 0
	s_lshl_b32 s15, s6, 25
	s_lshl_b32 s96, s8, 7
	s_add_u32 s15, s15, s96
	s_lshl_b32 s96, s5, 6
	s_add_u32 s15, s15, s96
	s_lshl_b32 s96, s11, 19
	s_add_u32 s15, s15, s96
	s_lshl_b32 s96, s51, 26
	s_add_u32 s15, s15, s96
	s_add_u32 s15, s15, 0xf000000
	s_add_u32 s44, s36, s15
	s_addc_u32 s45, s37, 0
	s_add_u32 s4, s3, 1
	s_sub_i32 s5, 4, s3
	s_movk_i32 s6, 0x2200
	s_mov_b32 s7, 0xffffde00
	s_movk_i32 s8, 0x80
	s_mov_b32 s9, 0xffffff80
	s_movk_i32 s15, 0x800
	s_mov_b32 s96, 0xfffff800
	s_cmp_eq_u32 s51, 0
	s_cselect_b32 s52, s4, s5
	s_cselect_b32 s53, s7, s6
	s_cselect_b32 s54, s9, s8
	s_cselect_b32 s13, s96, s15
	s_cselect_b32 s21, 124, 0
	s_waitcnt lgkmcnt(0)
	s_cmp_eq_u32 s51, 0
	s_cselect_b32 s24, s24, 0
	v_mov_b32_e32 v1, s10
	v_mul_f32_e32 v1, 0x3fb8aa3b, v1
	v_exp_f32_e32 v1, v1
	s_nop 0
	v_xor_b32_e32 v1, 0x80000000, v1
	s_nop 0
	v_readfirstlane_b32 s62, v1
	v_and_b32_e32 v116, 31, v175
	v_bfe_u32 v117, v175, 5, 1
	v_bfe_u32 v118, v175, 2, 2
	v_and_b32_e32 v119, 3, v175
	v_bfe_u32 v120, v175, 4, 1
	v_and_b32_e32 v121, 63, v175
	v_lshlrev_b32_e32 v122, 5, v120
	v_lshl_add_u32 v122, v119, 3, v122
	v_lshl_add_u32 v123, v117, 3, v118
	s_cmp_lt_u32 s3, 4
	s_cbranch_scc0 .Lm_setup_hi_2
	s_lshl_b32 s4, s3, 5
	v_add_u32_e32 v128, s4, v116
	v_lshlrev_b32_e32 v129, 4, v117
	v_lshrrev_b32_e32 v124, 4, v121
	v_and_b32_e32 v125, 15, v121
	v_lshlrev_b32_e32 v125, 4, v125
	v_lshlrev_b32_e32 v126, 3, v124
	s_lshl_b32 s4, s3, 5
	v_add_u32_e32 v127, s4, v126
	v_lshl_add_u32 v164, v127, 9, v125
	v_add_u32_e32 v164, 0x100, v164
	s_mul_i32 s4, s3, 0x2200
	s_add_u32 s4, s4, 0x11000
	v_mad_u32_u24 v166, v126, s59, v125
	v_add_u32_e32 v166, s4, v166
	v_mad_u32_u24 v167, v116, s59, v129
	v_add_u32_e32 v167, s4, v167
	v_lshlrev_b32_e32 v130, 3, v117
	v_mov_b32_e32 v131, 80
	v_mov_b32_e32 v131, 0x90
	v_lshlrev_b32_e32 v130, 4, v117
	v_mad_u32_u24 v168, v116, v131, v130
	v_add_u32_e32 v168, s4, v168
	v_lshrrev_b32_e32 v124, 2, v121
	v_and_b32_e32 v125, 3, v121
	v_lshlrev_b32_e32 v126, 5, v125
	v_lshlrev_b32_e32 v125, 4, v125
	v_mad_u32_u24 v169, v124, v131, v126
	v_add_u32_e32 v169, s4, v169
	s_lshl_b32 s4, s3, 5
	v_add_u32_e32 v124, s4, v124
	v_lshl_add_u32 v170, v124, 12, v125
	v_lshl_add_u32 v173, v124, 6, v125
	v_add_u32_e32 v171, 0x10000, v170
	v_mad_u32_u24 v165, v128, s59, v129
	v_mad_u32_u24 v130, v116, s59, v129
	v_add_u32_e32 v210, 0x1e800, v130
	v_lshlrev_b32_e32 v130, 2, v128
	v_add_u32_e32 v211, 0x22c00, v130
	v_lshlrev_b32_e32 v130, 3, v117
	v_lshl_add_u32 v212, v128, 12, v130
	s_lshl_b32 s4, s3, 7
	s_add_u32 s4, s4, 0x22c00
	v_add_u32_e32 v217, s4, v129
	s_lshl_b32 s4, s3, 7
	s_add_u32 s4, s4, 0x1d800
	v_add_u32_e32 v172, s4, v129
	s_cmp_eq_u32 s51, 0
	s_cselect_b32 s5, 124, 0
	s_lshl_b32 s4, s3, 7
	s_add_u32 s4, s4, s5
	s_add_u32 s4, s4, 0x22c00
	v_mov_b32_e32 v209, s4
	v_lshl_add_u32 v130, v117, 2, v118
	s_lshl_b32 s4, s3, 5
	v_add_u32_e32 v130, s4, v130
	v_mad_u32_u24 v130, v130, s60, v122
	v_add_u32_e32 v222, 0x19800, v130
	v_lshlrev_b32_e32 v129, 2, v117
	s_cmp_eq_u32 s51, 0
	s_cbranch_scc0 .Lm_mbwd_4
	v_add_u32_e32 v130, 0, v129
	v_cmp_le_u32_e64 s[64:65], v130, v116
	v_add_u32_e32 v130, 1, v129
	v_cmp_le_u32_e64 s[66:67], v130, v116
	v_add_u32_e32 v130, 2, v129
	v_cmp_le_u32_e64 s[68:69], v130, v116
	v_add_u32_e32 v130, 3, v129
	v_cmp_le_u32_e64 s[70:71], v130, v116
	v_add_u32_e32 v130, 8, v129
	v_cmp_le_u32_e64 s[72:73], v130, v116
	v_add_u32_e32 v130, 9, v129
	v_cmp_le_u32_e64 s[74:75], v130, v116
	v_add_u32_e32 v130, 10, v129
	v_cmp_le_u32_e64 s[76:77], v130, v116
	v_add_u32_e32 v130, 11, v129
	v_cmp_le_u32_e64 s[78:79], v130, v116
	v_add_u32_e32 v130, 16, v129
	v_cmp_le_u32_e64 s[80:81], v130, v116
	v_add_u32_e32 v130, 17, v129
	v_cmp_le_u32_e64 s[82:83], v130, v116
	v_add_u32_e32 v130, 18, v129
	v_cmp_le_u32_e64 s[84:85], v130, v116
	v_add_u32_e32 v130, 19, v129
	v_cmp_le_u32_e64 s[86:87], v130, v116
	v_add_u32_e32 v130, 24, v129
	v_cmp_le_u32_e64 s[88:89], v130, v116
	v_add_u32_e32 v130, 25, v129
	v_cmp_le_u32_e64 s[90:91], v130, v116
	v_add_u32_e32 v130, 26, v129
	v_cmp_le_u32_e64 s[92:93], v130, v116
	v_add_u32_e32 v130, 27, v129
	v_cmp_le_u32_e64 s[94:95], v130, v116
	s_branch .Lm_mdone_5

.Lm_loop:
	s_and_b32 s19, s50, 3
	s_lshl_b32 s19, s19, 9
	s_add_u32 s20, s50, 2
	s_and_b32 s20, s20, 3
	s_lshl_b32 s20, s20, 9
	s_cmp_lt_u32 s3, 4
	s_cbranch_scc0 .Lm_hi_14
	v_mov_b32_e32 v223, v165
	v_add_u32_e32 v224, s14, v217
	v_add_u32_e32 v208, s19, v172
	v_add_u32_e32 v216, s14, v209
	v_mov_b32_e32 v225, v222
	v_add_u32_e32 v1, s14, v211
	ds_read_b128 v[176:179], v167 offset:0
	ds_read_b128 v[180:183], v167 offset:32
	ds_read_b128 v[184:187], v167 offset:64
	ds_read_b128 v[188:191], v167 offset:96
	ds_read_b128 v[192:195], v167 offset:128
	ds_read_b128 v[196:199], v167 offset:160
	ds_read_b128 v[200:203], v167 offset:192
	ds_read_b128 v[204:207], v167 offset:224
	ds_read_b128 v[148:151], v223 offset:0
	ds_read_b128 v[152:155], v223 offset:32
	ds_read_b128 v[156:159], v223 offset:64
	ds_read_b128 v[160:163], v223 offset:96
	s_waitcnt lgkmcnt(11)
	s_waitcnt lgkmcnt(3)
	v_mfma_f32_32x32x16_bf16 v[116:131], v[148:151], v[176:179], 0
	ds_read_b128 v[148:151], v223 offset:128
	v_fma_f32 v76, v92, v3, v76
	v_fma_f32 v77, v93, v3, v77
	v_fma_f32 v78, v94, v3, v78
	s_waitcnt lgkmcnt(3)
	v_mfma_f32_32x32x16_bf16 v[116:131], v[152:155], v[180:183], v[116:131]
	ds_read_b128 v[152:155], v223 offset:160
	v_fma_f32 v79, v95, v3, v79
	v_fma_f32 v80, v96, v3, v80
	v_fma_f32 v81, v97, v3, v81
	s_waitcnt lgkmcnt(3)
	v_mfma_f32_32x32x16_bf16 v[116:131], v[156:159], v[184:187], v[116:131]
	ds_read_b128 v[156:159], v223 offset:192
	v_fma_f32 v82, v98, v3, v82
	v_fma_f32 v83, v99, v3, v83
	v_fma_f32 v84, v100, v3, v84
	s_waitcnt lgkmcnt(3)
	v_mfma_f32_32x32x16_bf16 v[116:131], v[160:163], v[188:191], v[116:131]
	ds_read_b128 v[160:163], v223 offset:224
	v_fma_f32 v85, v101, v3, v85
	v_fma_f32 v86, v102, v3, v86
	v_fma_f32 v87, v103, v3, v87
	ds_read_b128 v[234:237], v224 offset:0
	ds_read_b128 v[238:241], v224 offset:32
	ds_read_b128 v[242:245], v224 offset:64
	ds_read_b128 v[246:249], v224 offset:96
	ds_read_b32 v250, v1
	s_waitcnt lgkmcnt(8)
	v_mfma_f32_32x32x16_bf16 v[116:131], v[148:151], v[192:195], v[116:131]
	v_fma_f32 v88, v104, v3, v88
	v_fma_f32 v89, v105, v3, v89
	v_fma_f32 v90, v106, v3, v90
	s_waitcnt lgkmcnt(7)
	v_mfma_f32_32x32x16_bf16 v[116:131], v[152:155], v[196:199], v[116:131]
	v_fma_f32 v91, v107, v3, v91
	s_waitcnt lgkmcnt(6)
	v_mfma_f32_32x32x16_bf16 v[116:131], v[156:159], v[200:203], v[116:131]
	s_waitcnt lgkmcnt(5)
	v_mfma_f32_32x32x16_bf16 v[116:131], v[160:163], v[204:207], v[116:131]
	s_cmp_eq_u32 s52, 1
	s_cbranch_scc1 .Lm_yfin1_19
	ds_write_b128 v168, v[76:79] offset:0
	ds_write_b128 v168, v[80:83] offset:32
	ds_write_b128 v168, v[84:87] offset:64
	ds_write_b128 v168, v[88:91] offset:96
	global_load_dwordx4 v[76:79], v173, s[40:41]
	global_load_dwordx4 v[80:83], v173, s[40:41] offset:1024
	ds_read_b64_tr_b16 v[36:37], v225 offset:0
	ds_read_b64_tr_b16 v[38:39], v225 offset:512
	ds_read_b64_tr_b16 v[72:73], v225 offset:1024
	ds_read_b64_tr_b16 v[74:75], v225 offset:1536
	v_add_u32_e32 v223, s53, v223
	v_add_u32_e32 v208, s54, v208
	v_add_u32_e32 v216, s54, v216
	v_add_u32_e32 v225, s13, v225
	s_waitcnt lgkmcnt(9)
	s_waitcnt lgkmcnt(8)
	ds_read_b128 v[148:151], v223 offset:0
	ds_read_b128 v[152:155], v223 offset:32
	ds_read_b128 v[156:159], v223 offset:64
	ds_read_b128 v[160:163], v223 offset:96
	s_waitcnt lgkmcnt(3)
	v_mfma_f32_32x32x16_bf16 v[132:147], v[148:151], v[176:179], 0
	ds_read_b128 v[148:151], v223 offset:128
	ds_read_b128 v[92:95], v169 offset:0
	ds_read_b128 v[96:99], v169 offset:16
	ds_read_b128 v[100:103], v169 offset:2304
	ds_read_b128 v[104:107], v169 offset:2320
	v_sub_f32_e32 v234, v250, v234
	v_sub_f32_e32 v235, v250, v235
	v_sub_f32_e32 v236, v250, v236
	v_sub_f32_e32 v237, v250, v237
	v_sub_f32_e32 v238, v250, v238
	v_sub_f32_e32 v239, v250, v239
	v_sub_f32_e32 v240, v250, v240
	v_sub_f32_e32 v241, v250, v241
	v_sub_f32_e32 v242, v250, v242
	s_waitcnt lgkmcnt(7)
	v_mfma_f32_32x32x16_bf16 v[132:147], v[152:155], v[180:183], v[132:147]
	ds_read_b128 v[152:155], v223 offset:160
	v_sub_f32_e32 v243, v250, v243
	v_sub_f32_e32 v244, v250, v244
	v_sub_f32_e32 v245, v250, v245
	v_sub_f32_e32 v246, v250, v246
	v_sub_f32_e32 v247, v250, v247
	v_sub_f32_e32 v248, v250, v248
	v_sub_f32_e32 v249, v250, v249
	v_exp_f32_e32 v234, v234
	v_exp_f32_e32 v235, v235
	s_waitcnt lgkmcnt(7)
	v_mfma_f32_32x32x16_bf16 v[132:147], v[156:159], v[184:187], v[132:147]
	ds_read_b128 v[156:159], v223 offset:192
	v_exp_f32_e32 v236, v236
	v_exp_f32_e32 v237, v237
	v_exp_f32_e32 v238, v238
	v_exp_f32_e32 v239, v239
	v_exp_f32_e32 v240, v240
	v_exp_f32_e32 v241, v241
	v_exp_f32_e32 v242, v242
	v_exp_f32_e32 v243, v243
	v_exp_f32_e32 v244, v244
	s_waitcnt lgkmcnt(7)
	v_mfma_f32_32x32x16_bf16 v[132:147], v[160:163], v[188:191], v[132:147]
	ds_read_b128 v[160:163], v223 offset:224
	s_waitcnt lgkmcnt(3)
	s_waitcnt vmcnt(0)
	v_lshlrev_b32_e32 v108, 16, v76
	v_and_b32_e32 v109, 0xffff0000, v76
	v_fmac_f32_e32 v92, s24, v108
	v_fmac_f32_e32 v93, s24, v109
	v_lshlrev_b32_e32 v108, 16, v77
	v_and_b32_e32 v109, 0xffff0000, v77
	v_fmac_f32_e32 v94, s24, v108
	v_fmac_f32_e32 v95, s24, v109
	v_lshlrev_b32_e32 v108, 16, v78
	v_and_b32_e32 v109, 0xffff0000, v78
	v_fmac_f32_e32 v96, s24, v108
	v_fmac_f32_e32 v97, s24, v109
	v_lshlrev_b32_e32 v108, 16, v79
	v_and_b32_e32 v109, 0xffff0000, v79
	v_fmac_f32_e32 v98, s24, v108
	v_fmac_f32_e32 v99, s24, v109
	v_cvt_pk_bf16_f32 v92, v92, v93
	v_cvt_pk_bf16_f32 v93, v94, v95
	v_cvt_pk_bf16_f32 v94, v96, v97
	v_cvt_pk_bf16_f32 v95, v98, v99
	v_lshlrev_b32_e32 v108, 16, v80
	v_and_b32_e32 v109, 0xffff0000, v80
	v_fmac_f32_e32 v100, s24, v108
	v_fmac_f32_e32 v101, s24, v109
	v_lshlrev_b32_e32 v108, 16, v81
	v_and_b32_e32 v109, 0xffff0000, v81
	v_fmac_f32_e32 v102, s24, v108
	v_fmac_f32_e32 v103, s24, v109
	v_lshlrev_b32_e32 v108, 16, v82
	v_and_b32_e32 v109, 0xffff0000, v82
	v_fmac_f32_e32 v104, s24, v108
	v_fmac_f32_e32 v105, s24, v109
	v_lshlrev_b32_e32 v108, 16, v83
	v_and_b32_e32 v109, 0xffff0000, v83
	v_fmac_f32_e32 v106, s24, v108
	v_fmac_f32_e32 v107, s24, v109
	v_cvt_pk_bf16_f32 v100, v100, v101
	v_cvt_pk_bf16_f32 v101, v102, v103
	v_cvt_pk_bf16_f32 v102, v104, v105
	v_cvt_pk_bf16_f32 v103, v106, v107
	global_store_dwordx4 v170, v[92:95], s[44:45]
	global_store_dwordx4 v171, v[100:103], s[44:45]
	s_cmp_lg_u32 s50, 0
	s_cselect_b32 s4, s49, 0
	s_cselect_b32 s5, s55, 0
	s_cselect_b32 s6, s47, 0
	s_add_u32 s44, s44, s4
	s_addc_u32 s45, s45, s5
	s_add_u32 s40, s40, s6
	s_addc_u32 s41, s41, s5
	s_waitcnt vmcnt(12)
	v_exp_f32_e32 v245, v245
	v_exp_f32_e32 v246, v246
	v_exp_f32_e32 v247, v247
	v_exp_f32_e32 v248, v248
	v_exp_f32_e32 v249, v249
	v_mul_f32_e32 v116, v116, v234
	v_mul_f32_e32 v117, v117, v235
	v_mul_f32_e32 v118, v118, v236
	v_mul_f32_e32 v119, v119, v237
	v_mfma_f32_32x32x16_bf16 v[132:147], v[148:151], v[192:195], v[132:147]
	ds_write_b128 v166, v[40:43] offset:0
	ds_write_b128 v166, v[44:47] offset:272
	v_mul_f32_e32 v120, v120, v238
	v_mul_f32_e32 v121, v121, v239
	v_mul_f32_e32 v122, v122, v240
	v_mul_f32_e32 v123, v123, v241
	v_mul_f32_e32 v124, v124, v242
	v_mul_f32_e32 v125, v125, v243
	v_mul_f32_e32 v126, v126, v244
	v_mul_f32_e32 v127, v127, v245
	v_mul_f32_e32 v128, v128, v246
	s_waitcnt lgkmcnt(4)
	v_mfma_f32_32x32x16_bf16 v[132:147], v[152:155], v[196:199], v[132:147]
	ds_write_b128 v166, v[48:51] offset:544
	ds_write_b128 v166, v[52:55] offset:816
	v_mul_f32_e32 v129, v129, v247
	v_mul_f32_e32 v130, v130, v248
	v_mul_f32_e32 v131, v131, v249
	v_cndmask_b32_e64 v116, 0, v116, s[64:65]
	v_cndmask_b32_e64 v117, 0, v117, s[66:67]
	v_cndmask_b32_e64 v118, 0, v118, s[68:69]
	v_cndmask_b32_e64 v119, 0, v119, s[70:71]
	v_cndmask_b32_e64 v120, 0, v120, s[72:73]
	v_cndmask_b32_e64 v121, 0, v121, s[74:75]
	s_waitcnt lgkmcnt(5)
	v_mfma_f32_32x32x16_bf16 v[132:147], v[156:159], v[200:203], v[132:147]
	ds_write_b128 v166, v[56:59] offset:1088
	ds_write_b128 v166, v[60:63] offset:1360
	v_cndmask_b32_e64 v122, 0, v122, s[76:77]
	v_cndmask_b32_e64 v123, 0, v123, s[78:79]
	v_cndmask_b32_e64 v124, 0, v124, s[80:81]
	v_cndmask_b32_e64 v125, 0, v125, s[82:83]
	v_cndmask_b32_e64 v126, 0, v126, s[84:85]
	v_cndmask_b32_e64 v127, 0, v127, s[86:87]
	v_cndmask_b32_e64 v128, 0, v128, s[88:89]
	v_cndmask_b32_e64 v129, 0, v129, s[90:91]
	v_cndmask_b32_e64 v130, 0, v130, s[92:93]
	s_waitcnt lgkmcnt(6)
	v_mfma_f32_32x32x16_bf16 v[132:147], v[160:163], v[204:207], v[132:147]
	ds_write_b128 v166, v[64:67] offset:1632
	ds_write_b128 v166, v[68:71] offset:1904
	v_cndmask_b32_e64 v131, 0, v131, s[94:95]
	v_cvt_pk_bf16_f32 v116, v116, v117
	v_cvt_pk_bf16_f32 v117, v118, v119
	v_cvt_pk_bf16_f32 v118, v120, v121
	v_cvt_pk_bf16_f32 v119, v122, v123
	v_cvt_pk_bf16_f32 v120, v124, v125
	v_cvt_pk_bf16_f32 v121, v126, v127
	v_cvt_pk_bf16_f32 v122, v128, v129
	v_cvt_pk_bf16_f32 v123, v130, v131
	global_load_dwordx4 v[40:43], v164, s[38:39] offset:0
	global_load_dwordx4 v[44:47], v164, s[38:39] offset:512
	global_load_dwordx4 v[48:51], v164, s[38:39] offset:1024
	global_load_dwordx4 v[52:55], v164, s[38:39] offset:1536
	global_load_dwordx4 v[56:59], v164, s[38:39] offset:2048
	global_load_dwordx4 v[60:63], v164, s[38:39] offset:2560
	global_load_dwordx4 v[64:67], v164, s[38:39] offset:3072
	global_load_dwordx4 v[68:71], v164, s[38:39] offset:3584
	s_add_u32 s38, s38, s46
	s_addc_u32 s39, s39, s55
	s_waitcnt lgkmcnt(0)
	ds_read_b128 v[234:237], v208 offset:0
	ds_read_b128 v[238:241], v208 offset:32
	ds_read_b128 v[242:245], v208 offset:64
	ds_read_b128 v[246:249], v208 offset:96
	ds_read_b32 v251, v216
	v_mfma_f32_32x32x16_bf16 v[76:91], v[36:39], v[116:119], 0
	v_mfma_f32_32x32x16_bf16 v[76:91], v[72:75], v[120:123], v[76:91]
	s_cmp_eq_u32 s52, 2
	s_cbranch_scc1 .Lm_yfin2_20
	ds_read_b64_tr_b16 v[36:37], v225 offset:0
	ds_read_b64_tr_b16 v[38:39], v225 offset:512
	ds_read_b64_tr_b16 v[72:73], v225 offset:1024
	ds_read_b64_tr_b16 v[74:75], v225 offset:1536
	v_add_u32_e32 v223, s53, v223
	v_add_u32_e32 v208, s54, v208
	v_add_u32_e32 v216, s54, v216
	v_add_u32_e32 v225, s13, v225
	s_waitcnt lgkmcnt(4)
	ds_read_b128 v[148:151], v223 offset:0
	ds_read_b128 v[152:155], v223 offset:32
	ds_read_b128 v[156:159], v223 offset:64
	ds_read_b128 v[160:163], v223 offset:96
	s_waitcnt lgkmcnt(3)
	v_mfma_f32_32x32x16_bf16 v[116:131], v[148:151], v[176:179], 0
	ds_read_b128 v[148:151], v223 offset:128
	v_sub_f32_e32 v2, v250, v251
	v_exp_f32_e32 v2, v2
	s_nop 0
	v_mul_f32_e32 v234, v234, v2
	v_mul_f32_e32 v235, v235, v2
	s_waitcnt lgkmcnt(3)
	v_mfma_f32_32x32x16_bf16 v[116:131], v[152:155], v[180:183], v[116:131]
	ds_read_b128 v[152:155], v223 offset:160
	v_mul_f32_e32 v236, v236, v2
	v_mul_f32_e32 v237, v237, v2
	v_mul_f32_e32 v238, v238, v2
	v_mul_f32_e32 v239, v239, v2
	v_mul_f32_e32 v240, v240, v2
	s_waitcnt lgkmcnt(3)
	v_mfma_f32_32x32x16_bf16 v[116:131], v[156:159], v[184:187], v[116:131]
	ds_read_b128 v[156:159], v223 offset:192
	v_mul_f32_e32 v241, v241, v2
	v_mul_f32_e32 v242, v242, v2
	v_mul_f32_e32 v243, v243, v2
	v_mul_f32_e32 v244, v244, v2
	v_mul_f32_e32 v245, v245, v2
	v_mul_f32_e32 v246, v246, v2
	s_waitcnt lgkmcnt(3)
	v_mfma_f32_32x32x16_bf16 v[116:131], v[160:163], v[188:191], v[116:131]
	ds_read_b128 v[160:163], v223 offset:224
	v_mul_f32_e32 v247, v247, v2
	v_mul_f32_e32 v248, v248, v2
	v_mul_f32_e32 v249, v249, v2
	v_mul_f32_e32 v132, v132, v234
	v_mul_f32_e32 v133, v133, v235
	s_waitcnt lgkmcnt(3)
	v_mfma_f32_32x32x16_bf16 v[116:131], v[148:151], v[192:195], v[116:131]
	v_mul_f32_e32 v134, v134, v236
	v_mul_f32_e32 v135, v135, v237
	v_mul_f32_e32 v136, v136, v238
	v_mul_f32_e32 v137, v137, v239
	v_mul_f32_e32 v138, v138, v240
	s_waitcnt lgkmcnt(2)
	v_mfma_f32_32x32x16_bf16 v[116:131], v[152:155], v[196:199], v[116:131]
	v_mul_f32_e32 v139, v139, v241
	v_mul_f32_e32 v140, v140, v242
	v_mul_f32_e32 v141, v141, v243
	v_mul_f32_e32 v142, v142, v244
	v_mul_f32_e32 v143, v143, v245
	v_mul_f32_e32 v144, v144, v246
	s_waitcnt lgkmcnt(1)
	v_mfma_f32_32x32x16_bf16 v[116:131], v[156:159], v[200:203], v[116:131]
	v_mul_f32_e32 v145, v145, v247
	v_mul_f32_e32 v146, v146, v248
	v_mul_f32_e32 v147, v147, v249
	v_cvt_pk_bf16_f32 v132, v132, v133
	v_cvt_pk_bf16_f32 v133, v134, v135
	s_waitcnt lgkmcnt(0)
	v_mfma_f32_32x32x16_bf16 v[116:131], v[160:163], v[204:207], v[116:131]
	v_cvt_pk_bf16_f32 v134, v136, v137
	v_cvt_pk_bf16_f32 v135, v138, v139
	v_cvt_pk_bf16_f32 v136, v140, v141
	v_cvt_pk_bf16_f32 v137, v142, v143
	v_cvt_pk_bf16_f32 v138, v144, v145
	v_cvt_pk_bf16_f32 v139, v146, v147
	ds_read_b128 v[234:237], v208 offset:0
	ds_read_b128 v[238:241], v208 offset:32
	ds_read_b128 v[242:245], v208 offset:64
	ds_read_b128 v[246:249], v208 offset:96
	ds_read_b32 v251, v216
	v_mfma_f32_32x32x16_bf16 v[76:91], v[36:39], v[132:135], v[76:91]
	v_mfma_f32_32x32x16_bf16 v[76:91], v[72:75], v[136:139], v[76:91]
	s_cmp_eq_u32 s52, 3
	s_cbranch_scc1 .Lm_yfin3_21
	ds_read_b64_tr_b16 v[36:37], v225 offset:0
	ds_read_b64_tr_b16 v[38:39], v225 offset:512
	ds_read_b64_tr_b16 v[72:73], v225 offset:1024
	ds_read_b64_tr_b16 v[74:75], v225 offset:1536
	v_add_u32_e32 v223, s53, v223
	v_add_u32_e32 v208, s54, v208
	v_add_u32_e32 v216, s54, v216
	v_add_u32_e32 v225, s13, v225
	s_waitcnt lgkmcnt(4)
	ds_read_b128 v[148:151], v223 offset:0
	ds_read_b128 v[152:155], v223 offset:32
	ds_read_b128 v[156:159], v223 offset:64
	ds_read_b128 v[160:163], v223 offset:96
	s_waitcnt lgkmcnt(3)
	v_mfma_f32_32x32x16_bf16 v[132:147], v[148:151], v[176:179], 0
	ds_read_b128 v[148:151], v223 offset:128
	v_sub_f32_e32 v2, v250, v251
	v_exp_f32_e32 v2, v2
	s_nop 0
	v_mul_f32_e32 v234, v234, v2
	v_mul_f32_e32 v235, v235, v2
	s_waitcnt lgkmcnt(3)
	v_mfma_f32_32x32x16_bf16 v[132:147], v[152:155], v[180:183], v[132:147]
	ds_read_b128 v[152:155], v223 offset:160
	v_mul_f32_e32 v236, v236, v2
	v_mul_f32_e32 v237, v237, v2
	v_mul_f32_e32 v238, v238, v2
	v_mul_f32_e32 v239, v239, v2
	v_mul_f32_e32 v240, v240, v2
	s_waitcnt lgkmcnt(3)
	v_mfma_f32_32x32x16_bf16 v[132:147], v[156:159], v[184:187], v[132:147]
	ds_read_b128 v[156:159], v223 offset:192
	v_mul_f32_e32 v241, v241, v2
	v_mul_f32_e32 v242, v242, v2
	v_mul_f32_e32 v243, v243, v2
	v_mul_f32_e32 v244, v244, v2
	v_mul_f32_e32 v245, v245, v2
	v_mul_f32_e32 v246, v246, v2
	s_waitcnt lgkmcnt(3)
	v_mfma_f32_32x32x16_bf16 v[132:147], v[160:163], v[188:191], v[132:147]
	ds_read_b128 v[160:163], v223 offset:224
	v_mul_f32_e32 v247, v247, v2
	v_mul_f32_e32 v248, v248, v2
	v_mul_f32_e32 v249, v249, v2
	v_mul_f32_e32 v116, v116, v234
	v_mul_f32_e32 v117, v117, v235
	s_waitcnt lgkmcnt(3)
	v_mfma_f32_32x32x16_bf16 v[132:147], v[148:151], v[192:195], v[132:147]
	v_mul_f32_e32 v118, v118, v236
	v_mul_f32_e32 v119, v119, v237
	v_mul_f32_e32 v120, v120, v238
	v_mul_f32_e32 v121, v121, v239
	v_mul_f32_e32 v122, v122, v240
	s_waitcnt lgkmcnt(2)
	v_mfma_f32_32x32x16_bf16 v[132:147], v[152:155], v[196:199], v[132:147]
	v_mul_f32_e32 v123, v123, v241
	v_mul_f32_e32 v124, v124, v242
	v_mul_f32_e32 v125, v125, v243
	v_mul_f32_e32 v126, v126, v244
	v_mul_f32_e32 v127, v127, v245
	v_mul_f32_e32 v128, v128, v246
	s_waitcnt lgkmcnt(1)
	v_mfma_f32_32x32x16_bf16 v[132:147], v[156:159], v[200:203], v[132:147]
	v_mul_f32_e32 v129, v129, v247
	v_mul_f32_e32 v130, v130, v248
	v_mul_f32_e32 v131, v131, v249
	v_cvt_pk_bf16_f32 v116, v116, v117
	v_cvt_pk_bf16_f32 v117, v118, v119
	s_waitcnt lgkmcnt(0)
	v_mfma_f32_32x32x16_bf16 v[132:147], v[160:163], v[204:207], v[132:147]
	v_cvt_pk_bf16_f32 v118, v120, v121
	v_cvt_pk_bf16_f32 v119, v122, v123
	v_cvt_pk_bf16_f32 v120, v124, v125
	v_cvt_pk_bf16_f32 v121, v126, v127
	v_cvt_pk_bf16_f32 v122, v128, v129
	v_cvt_pk_bf16_f32 v123, v130, v131
	ds_read_b128 v[234:237], v208 offset:0
	ds_read_b128 v[238:241], v208 offset:32
	ds_read_b128 v[242:245], v208 offset:64
	ds_read_b128 v[246:249], v208 offset:96
	ds_read_b32 v251, v216
	v_mfma_f32_32x32x16_bf16 v[76:91], v[36:39], v[116:119], v[76:91]
	v_mfma_f32_32x32x16_bf16 v[76:91], v[72:75], v[120:123], v[76:91]
	ds_read_b64_tr_b16 v[36:37], v225 offset:0
	ds_read_b64_tr_b16 v[38:39], v225 offset:512
	ds_read_b64_tr_b16 v[72:73], v225 offset:1024
	ds_read_b64_tr_b16 v[74:75], v225 offset:1536
	s_waitcnt lgkmcnt(4)
	ds_read_b128 v[148:151], v210 offset:0
	ds_read_b128 v[152:155], v210 offset:32
	ds_read_b128 v[156:159], v210 offset:64
	ds_read_b128 v[160:163], v210 offset:96
	s_waitcnt lgkmcnt(3)
	v_mfma_f32_32x32x16_bf16 v[92:107], v[148:151], v[176:179], 0
	ds_read_b128 v[148:151], v210 offset:128
	v_sub_f32_e32 v2, v250, v251
	v_exp_f32_e32 v2, v2
	s_nop 0
	v_mul_f32_e32 v234, v234, v2
	v_mul_f32_e32 v235, v235, v2
	s_waitcnt lgkmcnt(3)
	v_mfma_f32_32x32x16_bf16 v[92:107], v[152:155], v[180:183], v[92:107]
	ds_read_b128 v[152:155], v210 offset:160
	v_mul_f32_e32 v236, v236, v2
	v_mul_f32_e32 v237, v237, v2
	v_mul_f32_e32 v238, v238, v2
	v_mul_f32_e32 v239, v239, v2
	v_mul_f32_e32 v240, v240, v2
	s_waitcnt lgkmcnt(3)
	v_mfma_f32_32x32x16_bf16 v[92:107], v[156:159], v[184:187], v[92:107]
	ds_read_b128 v[156:159], v210 offset:192
	v_mul_f32_e32 v241, v241, v2
	v_mul_f32_e32 v242, v242, v2
	v_mul_f32_e32 v243, v243, v2
	v_mul_f32_e32 v244, v244, v2
	v_mul_f32_e32 v245, v245, v2
	v_mul_f32_e32 v246, v246, v2
	s_waitcnt lgkmcnt(3)
	v_mfma_f32_32x32x16_bf16 v[92:107], v[160:163], v[188:191], v[92:107]
	ds_read_b128 v[160:163], v210 offset:224
	v_mul_f32_e32 v247, v247, v2
	v_mul_f32_e32 v248, v248, v2
	v_mul_f32_e32 v249, v249, v2
	v_mul_f32_e32 v132, v132, v234
	v_mul_f32_e32 v133, v133, v235
	s_waitcnt lgkmcnt(3)
	v_mfma_f32_32x32x16_bf16 v[92:107], v[148:151], v[192:195], v[92:107]
	v_mul_f32_e32 v134, v134, v236
	v_mul_f32_e32 v135, v135, v237
	v_mul_f32_e32 v136, v136, v238
	v_mul_f32_e32 v137, v137, v239
	v_mul_f32_e32 v138, v138, v240
	s_waitcnt lgkmcnt(2)
	v_mfma_f32_32x32x16_bf16 v[92:107], v[152:155], v[196:199], v[92:107]
	v_mul_f32_e32 v139, v139, v241
	v_mul_f32_e32 v140, v140, v242
	v_mul_f32_e32 v141, v141, v243
	v_mul_f32_e32 v142, v142, v244
	v_mul_f32_e32 v143, v143, v245
	v_mul_f32_e32 v144, v144, v246
	s_waitcnt lgkmcnt(1)
	v_mfma_f32_32x32x16_bf16 v[92:107], v[156:159], v[200:203], v[92:107]
	v_mul_f32_e32 v145, v145, v247
	v_mul_f32_e32 v146, v146, v248
	v_mul_f32_e32 v147, v147, v249
	v_cvt_pk_bf16_f32 v132, v132, v133
	v_cvt_pk_bf16_f32 v133, v134, v135
	s_waitcnt lgkmcnt(0)
	v_mfma_f32_32x32x16_bf16 v[92:107], v[160:163], v[204:207], v[92:107]
	v_cvt_pk_bf16_f32 v134, v136, v137
	v_cvt_pk_bf16_f32 v135, v138, v139
	v_cvt_pk_bf16_f32 v136, v140, v141
	v_cvt_pk_bf16_f32 v137, v142, v143
	v_cvt_pk_bf16_f32 v138, v144, v145
	v_cvt_pk_bf16_f32 v139, v146, v147
	v_mfma_f32_32x32x16_bf16 v[76:91], v[36:39], v[132:135], v[76:91]
	v_mfma_f32_32x32x16_bf16 v[76:91], v[72:75], v[136:139], v[76:91]
	s_branch .Lm_ydone_22
.Lm_yfin1_19:
	ds_write_b128 v168, v[76:79] offset:0
	ds_write_b128 v168, v[80:83] offset:32
	ds_write_b128 v168, v[84:87] offset:64
	ds_write_b128 v168, v[88:91] offset:96
	global_load_dwordx4 v[76:79], v173, s[40:41]
	global_load_dwordx4 v[80:83], v173, s[40:41] offset:1024
	s_waitcnt lgkmcnt(0)
	ds_read_b128 v[92:95], v169 offset:0
	ds_read_b128 v[96:99], v169 offset:16
	ds_read_b128 v[100:103], v169 offset:2304
	ds_read_b128 v[104:107], v169 offset:2320
	s_waitcnt lgkmcnt(0)
	s_waitcnt vmcnt(0)
	v_lshlrev_b32_e32 v108, 16, v76
	v_and_b32_e32 v109, 0xffff0000, v76
	v_fmac_f32_e32 v92, s24, v108
	v_fmac_f32_e32 v93, s24, v109
	v_lshlrev_b32_e32 v108, 16, v77
	v_and_b32_e32 v109, 0xffff0000, v77
	v_fmac_f32_e32 v94, s24, v108
	v_fmac_f32_e32 v95, s24, v109
	v_lshlrev_b32_e32 v108, 16, v78
	v_and_b32_e32 v109, 0xffff0000, v78
	v_fmac_f32_e32 v96, s24, v108
	v_fmac_f32_e32 v97, s24, v109
	v_lshlrev_b32_e32 v108, 16, v79
	v_and_b32_e32 v109, 0xffff0000, v79
	v_fmac_f32_e32 v98, s24, v108
	v_fmac_f32_e32 v99, s24, v109
	v_cvt_pk_bf16_f32 v92, v92, v93
	v_cvt_pk_bf16_f32 v93, v94, v95
	v_cvt_pk_bf16_f32 v94, v96, v97
	v_cvt_pk_bf16_f32 v95, v98, v99
	v_lshlrev_b32_e32 v108, 16, v80
	v_and_b32_e32 v109, 0xffff0000, v80
	v_fmac_f32_e32 v100, s24, v108
	v_fmac_f32_e32 v101, s24, v109
	v_lshlrev_b32_e32 v108, 16, v81
	v_and_b32_e32 v109, 0xffff0000, v81
	v_fmac_f32_e32 v102, s24, v108
	v_fmac_f32_e32 v103, s24, v109
	v_lshlrev_b32_e32 v108, 16, v82
	v_and_b32_e32 v109, 0xffff0000, v82
	v_fmac_f32_e32 v104, s24, v108
	v_fmac_f32_e32 v105, s24, v109
	v_lshlrev_b32_e32 v108, 16, v83
	v_and_b32_e32 v109, 0xffff0000, v83
	v_fmac_f32_e32 v106, s24, v108
	v_fmac_f32_e32 v107, s24, v109
	v_cvt_pk_bf16_f32 v100, v100, v101
	v_cvt_pk_bf16_f32 v101, v102, v103
	v_cvt_pk_bf16_f32 v102, v104, v105
	v_cvt_pk_bf16_f32 v103, v106, v107
	global_store_dwordx4 v170, v[92:95], s[44:45]
	global_store_dwordx4 v171, v[100:103], s[44:45]
	s_cmp_lg_u32 s50, 0
	s_cselect_b32 s4, s49, 0
	s_cselect_b32 s5, s55, 0
	s_cselect_b32 s6, s47, 0
	s_add_u32 s44, s44, s4
	s_addc_u32 s45, s45, s5
	s_add_u32 s40, s40, s6
	s_addc_u32 s41, s41, s5
	s_waitcnt vmcnt(16)
	ds_write_b128 v166, v[40:43] offset:0
	ds_write_b128 v166, v[44:47] offset:272
	ds_write_b128 v166, v[48:51] offset:544
	ds_write_b128 v166, v[52:55] offset:816
	ds_write_b128 v166, v[56:59] offset:1088
	ds_write_b128 v166, v[60:63] offset:1360
	ds_write_b128 v166, v[64:67] offset:1632
	ds_write_b128 v166, v[68:71] offset:1904
	global_load_dwordx4 v[40:43], v164, s[38:39] offset:0
	global_load_dwordx4 v[44:47], v164, s[38:39] offset:512
	global_load_dwordx4 v[48:51], v164, s[38:39] offset:1024
	global_load_dwordx4 v[52:55], v164, s[38:39] offset:1536
	global_load_dwordx4 v[56:59], v164, s[38:39] offset:2048
	global_load_dwordx4 v[60:63], v164, s[38:39] offset:2560
	global_load_dwordx4 v[64:67], v164, s[38:39] offset:3072
	global_load_dwordx4 v[68:71], v164, s[38:39] offset:3584
	s_add_u32 s38, s38, s46
	s_addc_u32 s39, s39, s55
	s_waitcnt lgkmcnt(0)
	ds_read_b64_tr_b16 v[36:37], v225 offset:0
	ds_read_b64_tr_b16 v[38:39], v225 offset:512
	ds_read_b64_tr_b16 v[72:73], v225 offset:1024
	ds_read_b64_tr_b16 v[74:75], v225 offset:1536
	ds_read_b128 v[148:151], v210 offset:0
	ds_read_b128 v[152:155], v210 offset:32
	ds_read_b128 v[156:159], v210 offset:64
	ds_read_b128 v[160:163], v210 offset:96
	s_waitcnt lgkmcnt(3)
	v_mfma_f32_32x32x16_bf16 v[92:107], v[148:151], v[176:179], 0
	ds_read_b128 v[148:151], v210 offset:128
	v_sub_f32_e32 v234, v250, v234
	v_sub_f32_e32 v235, v250, v235
	v_sub_f32_e32 v236, v250, v236
	v_sub_f32_e32 v237, v250, v237
	v_sub_f32_e32 v238, v250, v238
	v_sub_f32_e32 v239, v250, v239
	v_sub_f32_e32 v240, v250, v240
	v_sub_f32_e32 v241, v250, v241
	v_sub_f32_e32 v242, v250, v242
	s_waitcnt lgkmcnt(3)
	v_mfma_f32_32x32x16_bf16 v[92:107], v[152:155], v[180:183], v[92:107]
	ds_read_b128 v[152:155], v210 offset:160
	v_sub_f32_e32 v243, v250, v243
	v_sub_f32_e32 v244, v250, v244
	v_sub_f32_e32 v245, v250, v245
	v_sub_f32_e32 v246, v250, v246
	v_sub_f32_e32 v247, v250, v247
	v_sub_f32_e32 v248, v250, v248
	v_sub_f32_e32 v249, v250, v249
	v_exp_f32_e32 v234, v234
	v_exp_f32_e32 v235, v235
	s_waitcnt lgkmcnt(3)
	v_mfma_f32_32x32x16_bf16 v[92:107], v[156:159], v[184:187], v[92:107]
	ds_read_b128 v[156:159], v210 offset:192
	v_exp_f32_e32 v236, v236
	v_exp_f32_e32 v237, v237
	v_exp_f32_e32 v238, v238
	v_exp_f32_e32 v239, v239
	v_exp_f32_e32 v240, v240
	v_exp_f32_e32 v241, v241
	v_exp_f32_e32 v242, v242
	v_exp_f32_e32 v243, v243
	v_exp_f32_e32 v244, v244
	s_waitcnt lgkmcnt(3)
	v_mfma_f32_32x32x16_bf16 v[92:107], v[160:163], v[188:191], v[92:107]
	ds_read_b128 v[160:163], v210 offset:224
	v_exp_f32_e32 v245, v245
	v_exp_f32_e32 v246, v246
	v_exp_f32_e32 v247, v247
	v_exp_f32_e32 v248, v248
	v_exp_f32_e32 v249, v249
	v_mul_f32_e32 v116, v116, v234
	v_mul_f32_e32 v117, v117, v235
	v_mul_f32_e32 v118, v118, v236
	v_mul_f32_e32 v119, v119, v237
	s_waitcnt lgkmcnt(3)
	v_mfma_f32_32x32x16_bf16 v[92:107], v[148:151], v[192:195], v[92:107]
	v_mul_f32_e32 v120, v120, v238
	v_mul_f32_e32 v121, v121, v239
	v_mul_f32_e32 v122, v122, v240
	v_mul_f32_e32 v123, v123, v241
	v_mul_f32_e32 v124, v124, v242
	v_mul_f32_e32 v125, v125, v243
	v_mul_f32_e32 v126, v126, v244
	v_mul_f32_e32 v127, v127, v245
	v_mul_f32_e32 v128, v128, v246
	s_waitcnt lgkmcnt(2)
	v_mfma_f32_32x32x16_bf16 v[92:107], v[152:155], v[196:199], v[92:107]
	v_mul_f32_e32 v129, v129, v247
	v_mul_f32_e32 v130, v130, v248
	v_mul_f32_e32 v131, v131, v249
	v_cndmask_b32_e64 v116, 0, v116, s[64:65]
	v_cndmask_b32_e64 v117, 0, v117, s[66:67]
	v_cndmask_b32_e64 v118, 0, v118, s[68:69]
	v_cndmask_b32_e64 v119, 0, v119, s[70:71]
	v_cndmask_b32_e64 v120, 0, v120, s[72:73]
	v_cndmask_b32_e64 v121, 0, v121, s[74:75]
	s_waitcnt lgkmcnt(1)
	v_mfma_f32_32x32x16_bf16 v[92:107], v[156:159], v[200:203], v[92:107]
	v_cndmask_b32_e64 v122, 0, v122, s[76:77]
	v_cndmask_b32_e64 v123, 0, v123, s[78:79]
	v_cndmask_b32_e64 v124, 0, v124, s[80:81]
	v_cndmask_b32_e64 v125, 0, v125, s[82:83]
	v_cndmask_b32_e64 v126, 0, v126, s[84:85]
	v_cndmask_b32_e64 v127, 0, v127, s[86:87]
	v_cndmask_b32_e64 v128, 0, v128, s[88:89]
	v_cndmask_b32_e64 v129, 0, v129, s[90:91]
	v_cndmask_b32_e64 v130, 0, v130, s[92:93]
	s_waitcnt lgkmcnt(0)
	v_mfma_f32_32x32x16_bf16 v[92:107], v[160:163], v[204:207], v[92:107]
	v_cndmask_b32_e64 v131, 0, v131, s[94:95]
	v_cvt_pk_bf16_f32 v116, v116, v117
	v_cvt_pk_bf16_f32 v117, v118, v119
	v_cvt_pk_bf16_f32 v118, v120, v121
	v_cvt_pk_bf16_f32 v119, v122, v123
	v_cvt_pk_bf16_f32 v120, v124, v125
	v_cvt_pk_bf16_f32 v121, v126, v127
	v_cvt_pk_bf16_f32 v122, v128, v129
	v_cvt_pk_bf16_f32 v123, v130, v131
	v_mfma_f32_32x32x16_bf16 v[76:91], v[36:39], v[116:119], 0
	v_mfma_f32_32x32x16_bf16 v[76:91], v[72:75], v[120:123], v[76:91]
	s_waitcnt vmcnt(10)
	v_mul_f32_e32 v132, s62, v146
	v_mul_f32_e32 v133, s62, v147
	v_add_f32_e32 v134, v132, v133
	v_and_b32_e32 v140, 63, v175
	v_lshrrev_b32_e32 v142, 4, v140
	v_add_f32_dpp v134, v134, v134 row_shr:1 row_mask:0xf bank_mask:0xf bound_ctrl:0
	s_nop 1
	v_add_f32_dpp v134, v134, v134 row_shr:2 row_mask:0xf bank_mask:0xf bound_ctrl:0
	s_nop 1
	v_add_f32_dpp v134, v134, v134 row_shr:4 row_mask:0xf bank_mask:0xf bound_ctrl:0
	s_nop 1
	v_add_f32_dpp v134, v134, v134 row_shr:8 row_mask:0xf bank_mask:0xf bound_ctrl:0
	s_nop 1
	v_add_f32_dpp v134, v134, v134 row_bcast:15 row_mask:0xa bank_mask:0xf
	s_nop 1
	v_add_f32_dpp v134, v134, v134 row_bcast:31 row_mask:0xc bank_mask:0xf
	v_lshlrev_b32_e32 v140, 3, v140
	v_lshlrev_b32_e32 v142, 7, v142
	v_readlane_b32 s97, v134, 63
	v_sub_f32_e32 v138, v134, v133
	v_mov_b32_e32 v139, v134
	v_add_u32_e32 v143, 0x1d800, v140
	v_add_u32_e32 v143, s20, v143
	s_cmp_eq_u32 s51, 0
	s_cbranch_scc1 .Lm_scanf_23
	v_sub_f32_e32 v138, s97, v138
	v_sub_f32_e32 v139, s97, v139
	v_fma_f32 v138, v146, s62, v138
	v_fma_f32 v139, v147, s62, v139

.Lm_stepdone_15:
	s_waitcnt lgkmcnt(0)
	s_barrier
	s_mov_b32 s14, s16
	s_mov_b32 s16, s17
	s_add_u32 s17, s17, 1280
	s_cmpk_eq_u32 s17, 5120
	s_cselect_b32 s17, 0, s17
	s_add_u32 s50, s50, 1
	s_and_b32 s19, s50, 3
	s_lshl_b32 s19, s19, 9
	s_add_u32 s20, s50, 2
	s_and_b32 s20, s20, 3
	s_lshl_b32 s20, s20, 9
	s_cmp_lt_u32 s3, 4
	s_cbranch_scc0 .Lm_hi_25
	v_mov_b32_e32 v223, v165
	v_add_u32_e32 v224, s14, v217
	v_add_u32_e32 v208, s19, v172
	v_add_u32_e32 v216, s14, v209
	v_mov_b32_e32 v225, v222
	v_add_u32_e32 v1, s14, v211
	ds_read_b128 v[176:179], v167 offset:0
	ds_read_b128 v[180:183], v167 offset:32
	ds_read_b128 v[184:187], v167 offset:64
	ds_read_b128 v[188:191], v167 offset:96
	ds_read_b128 v[192:195], v167 offset:128
	ds_read_b128 v[196:199], v167 offset:160
	ds_read_b128 v[200:203], v167 offset:192
	ds_read_b128 v[204:207], v167 offset:224
	ds_read_b128 v[148:151], v223 offset:34816
	ds_read_b128 v[152:155], v223 offset:34848
	ds_read_b128 v[156:159], v223 offset:34880
	ds_read_b128 v[160:163], v223 offset:34912
	s_waitcnt lgkmcnt(11)
	s_waitcnt lgkmcnt(3)
	v_mfma_f32_32x32x16_bf16 v[116:131], v[148:151], v[176:179], 0
	ds_read_b128 v[148:151], v223 offset:34944
	v_fma_f32 v76, v92, v3, v76
	v_fma_f32 v77, v93, v3, v77
	v_fma_f32 v78, v94, v3, v78
	s_waitcnt lgkmcnt(3)
	v_mfma_f32_32x32x16_bf16 v[116:131], v[152:155], v[180:183], v[116:131]
	ds_read_b128 v[152:155], v223 offset:34976
	v_fma_f32 v79, v95, v3, v79
	v_fma_f32 v80, v96, v3, v80
	v_fma_f32 v81, v97, v3, v81
	s_waitcnt lgkmcnt(3)
	v_mfma_f32_32x32x16_bf16 v[116:131], v[156:159], v[184:187], v[116:131]
	ds_read_b128 v[156:159], v223 offset:35008
	v_fma_f32 v82, v98, v3, v82
	v_fma_f32 v83, v99, v3, v83
	v_fma_f32 v84, v100, v3, v84
	s_waitcnt lgkmcnt(3)
	v_mfma_f32_32x32x16_bf16 v[116:131], v[160:163], v[188:191], v[116:131]
	ds_read_b128 v[160:163], v223 offset:35040
	v_fma_f32 v85, v101, v3, v85
	v_fma_f32 v86, v102, v3, v86
	v_fma_f32 v87, v103, v3, v87
	ds_read_b128 v[234:237], v224 offset:0
	ds_read_b128 v[238:241], v224 offset:32
	ds_read_b128 v[242:245], v224 offset:64
	ds_read_b128 v[246:249], v224 offset:96
	ds_read_b32 v250, v1
	s_waitcnt lgkmcnt(8)
	v_mfma_f32_32x32x16_bf16 v[116:131], v[148:151], v[192:195], v[116:131]
	v_fma_f32 v88, v104, v3, v88
	v_fma_f32 v89, v105, v3, v89
	v_fma_f32 v90, v106, v3, v90
	s_waitcnt lgkmcnt(7)
	v_mfma_f32_32x32x16_bf16 v[116:131], v[152:155], v[196:199], v[116:131]
	v_fma_f32 v91, v107, v3, v91
	s_waitcnt lgkmcnt(6)
	v_mfma_f32_32x32x16_bf16 v[116:131], v[156:159], v[200:203], v[116:131]
	s_waitcnt lgkmcnt(5)
	v_mfma_f32_32x32x16_bf16 v[116:131], v[160:163], v[204:207], v[116:131]
	s_cmp_eq_u32 s52, 1
	s_cbranch_scc1 .Lm_yfin1_30
	ds_write_b128 v168, v[76:79] offset:0
	ds_write_b128 v168, v[80:83] offset:32
	ds_write_b128 v168, v[84:87] offset:64
	ds_write_b128 v168, v[88:91] offset:96
	global_load_dwordx4 v[76:79], v173, s[40:41]
	global_load_dwordx4 v[80:83], v173, s[40:41] offset:1024
	ds_read_b64_tr_b16 v[36:37], v225 offset:43008
	ds_read_b64_tr_b16 v[38:39], v225 offset:43520
	ds_read_b64_tr_b16 v[72:73], v225 offset:44032
	ds_read_b64_tr_b16 v[74:75], v225 offset:44544
	v_add_u32_e32 v223, s53, v223
	v_add_u32_e32 v208, s54, v208
	v_add_u32_e32 v216, s54, v216
	v_add_u32_e32 v225, s13, v225
	s_waitcnt lgkmcnt(9)
	s_waitcnt lgkmcnt(8)
	ds_read_b128 v[148:151], v223 offset:34816
	ds_read_b128 v[152:155], v223 offset:34848
	ds_read_b128 v[156:159], v223 offset:34880
	ds_read_b128 v[160:163], v223 offset:34912
	s_waitcnt lgkmcnt(3)
	v_mfma_f32_32x32x16_bf16 v[132:147], v[148:151], v[176:179], 0
	ds_read_b128 v[148:151], v223 offset:34944
	ds_read_b128 v[92:95], v169 offset:0
	ds_read_b128 v[96:99], v169 offset:16
	ds_read_b128 v[100:103], v169 offset:2304
	ds_read_b128 v[104:107], v169 offset:2320
	v_sub_f32_e32 v234, v250, v234
	v_sub_f32_e32 v235, v250, v235
	v_sub_f32_e32 v236, v250, v236
	v_sub_f32_e32 v237, v250, v237
	v_sub_f32_e32 v238, v250, v238
	v_sub_f32_e32 v239, v250, v239
	v_sub_f32_e32 v240, v250, v240
	v_sub_f32_e32 v241, v250, v241
	v_sub_f32_e32 v242, v250, v242
	s_waitcnt lgkmcnt(7)
	v_mfma_f32_32x32x16_bf16 v[132:147], v[152:155], v[180:183], v[132:147]
	ds_read_b128 v[152:155], v223 offset:34976
	v_sub_f32_e32 v243, v250, v243
	v_sub_f32_e32 v244, v250, v244
	v_sub_f32_e32 v245, v250, v245
	v_sub_f32_e32 v246, v250, v246
	v_sub_f32_e32 v247, v250, v247
	v_sub_f32_e32 v248, v250, v248
	v_sub_f32_e32 v249, v250, v249
	v_exp_f32_e32 v234, v234
	v_exp_f32_e32 v235, v235
	s_waitcnt lgkmcnt(7)
	v_mfma_f32_32x32x16_bf16 v[132:147], v[156:159], v[184:187], v[132:147]
	ds_read_b128 v[156:159], v223 offset:35008
	v_exp_f32_e32 v236, v236
	v_exp_f32_e32 v237, v237
	v_exp_f32_e32 v238, v238
	v_exp_f32_e32 v239, v239
	v_exp_f32_e32 v240, v240
	v_exp_f32_e32 v241, v241
	v_exp_f32_e32 v242, v242
	v_exp_f32_e32 v243, v243
	v_exp_f32_e32 v244, v244
	s_waitcnt lgkmcnt(7)
	v_mfma_f32_32x32x16_bf16 v[132:147], v[160:163], v[188:191], v[132:147]
	ds_read_b128 v[160:163], v223 offset:35040
	s_waitcnt lgkmcnt(3)
	s_waitcnt vmcnt(0)
	v_lshlrev_b32_e32 v108, 16, v76
	v_and_b32_e32 v109, 0xffff0000, v76
	v_fmac_f32_e32 v92, s24, v108
	v_fmac_f32_e32 v93, s24, v109
	v_lshlrev_b32_e32 v108, 16, v77
	v_and_b32_e32 v109, 0xffff0000, v77
	v_fmac_f32_e32 v94, s24, v108
	v_fmac_f32_e32 v95, s24, v109
	v_lshlrev_b32_e32 v108, 16, v78
	v_and_b32_e32 v109, 0xffff0000, v78
	v_fmac_f32_e32 v96, s24, v108
	v_fmac_f32_e32 v97, s24, v109
	v_lshlrev_b32_e32 v108, 16, v79
	v_and_b32_e32 v109, 0xffff0000, v79
	v_fmac_f32_e32 v98, s24, v108
	v_fmac_f32_e32 v99, s24, v109
	v_cvt_pk_bf16_f32 v92, v92, v93
	v_cvt_pk_bf16_f32 v93, v94, v95
	v_cvt_pk_bf16_f32 v94, v96, v97
	v_cvt_pk_bf16_f32 v95, v98, v99
	v_lshlrev_b32_e32 v108, 16, v80
	v_and_b32_e32 v109, 0xffff0000, v80
	v_fmac_f32_e32 v100, s24, v108
	v_fmac_f32_e32 v101, s24, v109
	v_lshlrev_b32_e32 v108, 16, v81
	v_and_b32_e32 v109, 0xffff0000, v81
	v_fmac_f32_e32 v102, s24, v108
	v_fmac_f32_e32 v103, s24, v109
	v_lshlrev_b32_e32 v108, 16, v82
	v_and_b32_e32 v109, 0xffff0000, v82
	v_fmac_f32_e32 v104, s24, v108
	v_fmac_f32_e32 v105, s24, v109
	v_lshlrev_b32_e32 v108, 16, v83
	v_and_b32_e32 v109, 0xffff0000, v83
	v_fmac_f32_e32 v106, s24, v108
	v_fmac_f32_e32 v107, s24, v109
	v_cvt_pk_bf16_f32 v100, v100, v101
	v_cvt_pk_bf16_f32 v101, v102, v103
	v_cvt_pk_bf16_f32 v102, v104, v105
	v_cvt_pk_bf16_f32 v103, v106, v107
	global_store_dwordx4 v170, v[92:95], s[44:45]
	global_store_dwordx4 v171, v[100:103], s[44:45]
	s_cmp_lg_u32 s50, 0
	s_cselect_b32 s4, s49, 0
	s_cselect_b32 s5, s55, 0
	s_cselect_b32 s6, s47, 0
	s_add_u32 s44, s44, s4
	s_addc_u32 s45, s45, s5
	s_add_u32 s40, s40, s6
	s_addc_u32 s41, s41, s5
	s_waitcnt vmcnt(12)
	v_exp_f32_e32 v245, v245
	v_exp_f32_e32 v246, v246
	v_exp_f32_e32 v247, v247
	v_exp_f32_e32 v248, v248
	v_exp_f32_e32 v249, v249
	v_mul_f32_e32 v116, v116, v234
	v_mul_f32_e32 v117, v117, v235
	v_mul_f32_e32 v118, v118, v236
	v_mul_f32_e32 v119, v119, v237
	v_mfma_f32_32x32x16_bf16 v[132:147], v[148:151], v[192:195], v[132:147]
	ds_write_b128 v166, v[4:7] offset:0
	ds_write_b128 v166, v[8:11] offset:272
	v_mul_f32_e32 v120, v120, v238
	v_mul_f32_e32 v121, v121, v239
	v_mul_f32_e32 v122, v122, v240
	v_mul_f32_e32 v123, v123, v241
	v_mul_f32_e32 v124, v124, v242
	v_mul_f32_e32 v125, v125, v243
	v_mul_f32_e32 v126, v126, v244
	v_mul_f32_e32 v127, v127, v245
	v_mul_f32_e32 v128, v128, v246
	s_waitcnt lgkmcnt(4)
	v_mfma_f32_32x32x16_bf16 v[132:147], v[152:155], v[196:199], v[132:147]
	ds_write_b128 v166, v[12:15] offset:544
	ds_write_b128 v166, v[16:19] offset:816
	v_mul_f32_e32 v129, v129, v247
	v_mul_f32_e32 v130, v130, v248
	v_mul_f32_e32 v131, v131, v249
	v_cndmask_b32_e64 v116, 0, v116, s[64:65]
	v_cndmask_b32_e64 v117, 0, v117, s[66:67]
	v_cndmask_b32_e64 v118, 0, v118, s[68:69]
	v_cndmask_b32_e64 v119, 0, v119, s[70:71]
	v_cndmask_b32_e64 v120, 0, v120, s[72:73]
	v_cndmask_b32_e64 v121, 0, v121, s[74:75]
	s_waitcnt lgkmcnt(5)
	v_mfma_f32_32x32x16_bf16 v[132:147], v[156:159], v[200:203], v[132:147]
	ds_write_b128 v166, v[20:23] offset:1088
	ds_write_b128 v166, v[24:27] offset:1360
	v_cndmask_b32_e64 v122, 0, v122, s[76:77]
	v_cndmask_b32_e64 v123, 0, v123, s[78:79]
	v_cndmask_b32_e64 v124, 0, v124, s[80:81]
	v_cndmask_b32_e64 v125, 0, v125, s[82:83]
	v_cndmask_b32_e64 v126, 0, v126, s[84:85]
	v_cndmask_b32_e64 v127, 0, v127, s[86:87]
	v_cndmask_b32_e64 v128, 0, v128, s[88:89]
	v_cndmask_b32_e64 v129, 0, v129, s[90:91]
	v_cndmask_b32_e64 v130, 0, v130, s[92:93]
	s_waitcnt lgkmcnt(6)
	v_mfma_f32_32x32x16_bf16 v[132:147], v[160:163], v[204:207], v[132:147]
	ds_write_b128 v166, v[28:31] offset:1632
	ds_write_b128 v166, v[32:35] offset:1904
	v_cndmask_b32_e64 v131, 0, v131, s[94:95]
	v_cvt_pk_bf16_f32 v116, v116, v117
	v_cvt_pk_bf16_f32 v117, v118, v119
	v_cvt_pk_bf16_f32 v118, v120, v121
	v_cvt_pk_bf16_f32 v119, v122, v123
	v_cvt_pk_bf16_f32 v120, v124, v125
	v_cvt_pk_bf16_f32 v121, v126, v127
	v_cvt_pk_bf16_f32 v122, v128, v129
	v_cvt_pk_bf16_f32 v123, v130, v131
	global_load_dwordx4 v[4:7], v164, s[38:39] offset:0
	global_load_dwordx4 v[8:11], v164, s[38:39] offset:512
	global_load_dwordx4 v[12:15], v164, s[38:39] offset:1024
	global_load_dwordx4 v[16:19], v164, s[38:39] offset:1536
	global_load_dwordx4 v[20:23], v164, s[38:39] offset:2048
	global_load_dwordx4 v[24:27], v164, s[38:39] offset:2560
	global_load_dwordx4 v[28:31], v164, s[38:39] offset:3072
	global_load_dwordx4 v[32:35], v164, s[38:39] offset:3584
	s_add_u32 s38, s38, s46
	s_addc_u32 s39, s39, s55
	s_waitcnt lgkmcnt(0)
	ds_read_b128 v[234:237], v208 offset:0
	ds_read_b128 v[238:241], v208 offset:32
	ds_read_b128 v[242:245], v208 offset:64
	ds_read_b128 v[246:249], v208 offset:96
	ds_read_b32 v251, v216
	v_mfma_f32_32x32x16_bf16 v[76:91], v[36:39], v[116:119], 0
	v_mfma_f32_32x32x16_bf16 v[76:91], v[72:75], v[120:123], v[76:91]
	s_cmp_eq_u32 s52, 2
	s_cbranch_scc1 .Lm_yfin2_31
	ds_read_b64_tr_b16 v[36:37], v225 offset:43008
	ds_read_b64_tr_b16 v[38:39], v225 offset:43520
	ds_read_b64_tr_b16 v[72:73], v225 offset:44032
	ds_read_b64_tr_b16 v[74:75], v225 offset:44544
	v_add_u32_e32 v223, s53, v223
	v_add_u32_e32 v208, s54, v208
	v_add_u32_e32 v216, s54, v216
	v_add_u32_e32 v225, s13, v225
	s_waitcnt lgkmcnt(4)
	ds_read_b128 v[148:151], v223 offset:34816
	ds_read_b128 v[152:155], v223 offset:34848
	ds_read_b128 v[156:159], v223 offset:34880
	ds_read_b128 v[160:163], v223 offset:34912
	s_waitcnt lgkmcnt(3)
	v_mfma_f32_32x32x16_bf16 v[116:131], v[148:151], v[176:179], 0
	ds_read_b128 v[148:151], v223 offset:34944
	v_sub_f32_e32 v2, v250, v251
	v_exp_f32_e32 v2, v2
	s_nop 0
	v_mul_f32_e32 v234, v234, v2
	v_mul_f32_e32 v235, v235, v2
	s_waitcnt lgkmcnt(3)
	v_mfma_f32_32x32x16_bf16 v[116:131], v[152:155], v[180:183], v[116:131]
	ds_read_b128 v[152:155], v223 offset:34976
	v_mul_f32_e32 v236, v236, v2
	v_mul_f32_e32 v237, v237, v2
	v_mul_f32_e32 v238, v238, v2
	v_mul_f32_e32 v239, v239, v2
	v_mul_f32_e32 v240, v240, v2
	s_waitcnt lgkmcnt(3)
	v_mfma_f32_32x32x16_bf16 v[116:131], v[156:159], v[184:187], v[116:131]
	ds_read_b128 v[156:159], v223 offset:35008
	v_mul_f32_e32 v241, v241, v2
	v_mul_f32_e32 v242, v242, v2
	v_mul_f32_e32 v243, v243, v2
	v_mul_f32_e32 v244, v244, v2
	v_mul_f32_e32 v245, v245, v2
	v_mul_f32_e32 v246, v246, v2
	s_waitcnt lgkmcnt(3)
	v_mfma_f32_32x32x16_bf16 v[116:131], v[160:163], v[188:191], v[116:131]
	ds_read_b128 v[160:163], v223 offset:35040
	v_mul_f32_e32 v247, v247, v2
	v_mul_f32_e32 v248, v248, v2
	v_mul_f32_e32 v249, v249, v2
	v_mul_f32_e32 v132, v132, v234
	v_mul_f32_e32 v133, v133, v235
	s_waitcnt lgkmcnt(3)
	v_mfma_f32_32x32x16_bf16 v[116:131], v[148:151], v[192:195], v[116:131]
	v_mul_f32_e32 v134, v134, v236
	v_mul_f32_e32 v135, v135, v237
	v_mul_f32_e32 v136, v136, v238
	v_mul_f32_e32 v137, v137, v239
	v_mul_f32_e32 v138, v138, v240
	s_waitcnt lgkmcnt(2)
	v_mfma_f32_32x32x16_bf16 v[116:131], v[152:155], v[196:199], v[116:131]
	v_mul_f32_e32 v139, v139, v241
	v_mul_f32_e32 v140, v140, v242
	v_mul_f32_e32 v141, v141, v243
	v_mul_f32_e32 v142, v142, v244
	v_mul_f32_e32 v143, v143, v245
	v_mul_f32_e32 v144, v144, v246
	s_waitcnt lgkmcnt(1)
	v_mfma_f32_32x32x16_bf16 v[116:131], v[156:159], v[200:203], v[116:131]
	v_mul_f32_e32 v145, v145, v247
	v_mul_f32_e32 v146, v146, v248
	v_mul_f32_e32 v147, v147, v249
	v_cvt_pk_bf16_f32 v132, v132, v133
	v_cvt_pk_bf16_f32 v133, v134, v135
	s_waitcnt lgkmcnt(0)
	v_mfma_f32_32x32x16_bf16 v[116:131], v[160:163], v[204:207], v[116:131]
	v_cvt_pk_bf16_f32 v134, v136, v137
	v_cvt_pk_bf16_f32 v135, v138, v139
	v_cvt_pk_bf16_f32 v136, v140, v141
	v_cvt_pk_bf16_f32 v137, v142, v143
	v_cvt_pk_bf16_f32 v138, v144, v145
	v_cvt_pk_bf16_f32 v139, v146, v147
	ds_read_b128 v[234:237], v208 offset:0
	ds_read_b128 v[238:241], v208 offset:32
	ds_read_b128 v[242:245], v208 offset:64
	ds_read_b128 v[246:249], v208 offset:96
	ds_read_b32 v251, v216
	v_mfma_f32_32x32x16_bf16 v[76:91], v[36:39], v[132:135], v[76:91]
	v_mfma_f32_32x32x16_bf16 v[76:91], v[72:75], v[136:139], v[76:91]
	s_cmp_eq_u32 s52, 3
	s_cbranch_scc1 .Lm_yfin3_32
	ds_read_b64_tr_b16 v[36:37], v225 offset:43008
	ds_read_b64_tr_b16 v[38:39], v225 offset:43520
	ds_read_b64_tr_b16 v[72:73], v225 offset:44032
	ds_read_b64_tr_b16 v[74:75], v225 offset:44544
	v_add_u32_e32 v223, s53, v223
	v_add_u32_e32 v208, s54, v208
	v_add_u32_e32 v216, s54, v216
	v_add_u32_e32 v225, s13, v225
	s_waitcnt lgkmcnt(4)
	ds_read_b128 v[148:151], v223 offset:34816
	ds_read_b128 v[152:155], v223 offset:34848
	ds_read_b128 v[156:159], v223 offset:34880
	ds_read_b128 v[160:163], v223 offset:34912
	s_waitcnt lgkmcnt(3)
	v_mfma_f32_32x32x16_bf16 v[132:147], v[148:151], v[176:179], 0
	ds_read_b128 v[148:151], v223 offset:34944
	v_sub_f32_e32 v2, v250, v251
	v_exp_f32_e32 v2, v2
	s_nop 0
	v_mul_f32_e32 v234, v234, v2
	v_mul_f32_e32 v235, v235, v2
	s_waitcnt lgkmcnt(3)
	v_mfma_f32_32x32x16_bf16 v[132:147], v[152:155], v[180:183], v[132:147]
	ds_read_b128 v[152:155], v223 offset:34976
	v_mul_f32_e32 v236, v236, v2
	v_mul_f32_e32 v237, v237, v2
	v_mul_f32_e32 v238, v238, v2
	v_mul_f32_e32 v239, v239, v2
	v_mul_f32_e32 v240, v240, v2
	s_waitcnt lgkmcnt(3)
	v_mfma_f32_32x32x16_bf16 v[132:147], v[156:159], v[184:187], v[132:147]
	ds_read_b128 v[156:159], v223 offset:35008
	v_mul_f32_e32 v241, v241, v2
	v_mul_f32_e32 v242, v242, v2
	v_mul_f32_e32 v243, v243, v2
	v_mul_f32_e32 v244, v244, v2
	v_mul_f32_e32 v245, v245, v2
	v_mul_f32_e32 v246, v246, v2
	s_waitcnt lgkmcnt(3)
	v_mfma_f32_32x32x16_bf16 v[132:147], v[160:163], v[188:191], v[132:147]
	ds_read_b128 v[160:163], v223 offset:35040
	v_mul_f32_e32 v247, v247, v2
	v_mul_f32_e32 v248, v248, v2
	v_mul_f32_e32 v249, v249, v2
	v_mul_f32_e32 v116, v116, v234
	v_mul_f32_e32 v117, v117, v235
	s_waitcnt lgkmcnt(3)
	v_mfma_f32_32x32x16_bf16 v[132:147], v[148:151], v[192:195], v[132:147]
	v_mul_f32_e32 v118, v118, v236
	v_mul_f32_e32 v119, v119, v237
	v_mul_f32_e32 v120, v120, v238
	v_mul_f32_e32 v121, v121, v239
	v_mul_f32_e32 v122, v122, v240
	s_waitcnt lgkmcnt(2)
	v_mfma_f32_32x32x16_bf16 v[132:147], v[152:155], v[196:199], v[132:147]
	v_mul_f32_e32 v123, v123, v241
	v_mul_f32_e32 v124, v124, v242
	v_mul_f32_e32 v125, v125, v243
	v_mul_f32_e32 v126, v126, v244
	v_mul_f32_e32 v127, v127, v245
	v_mul_f32_e32 v128, v128, v246
	s_waitcnt lgkmcnt(1)
	v_mfma_f32_32x32x16_bf16 v[132:147], v[156:159], v[200:203], v[132:147]
	v_mul_f32_e32 v129, v129, v247
	v_mul_f32_e32 v130, v130, v248
	v_mul_f32_e32 v131, v131, v249
	v_cvt_pk_bf16_f32 v116, v116, v117
	v_cvt_pk_bf16_f32 v117, v118, v119
	s_waitcnt lgkmcnt(0)
	v_mfma_f32_32x32x16_bf16 v[132:147], v[160:163], v[204:207], v[132:147]
	v_cvt_pk_bf16_f32 v118, v120, v121
	v_cvt_pk_bf16_f32 v119, v122, v123
	v_cvt_pk_bf16_f32 v120, v124, v125
	v_cvt_pk_bf16_f32 v121, v126, v127
	v_cvt_pk_bf16_f32 v122, v128, v129
	v_cvt_pk_bf16_f32 v123, v130, v131
	ds_read_b128 v[234:237], v208 offset:0
	ds_read_b128 v[238:241], v208 offset:32
	ds_read_b128 v[242:245], v208 offset:64
	ds_read_b128 v[246:249], v208 offset:96
	ds_read_b32 v251, v216
	v_mfma_f32_32x32x16_bf16 v[76:91], v[36:39], v[116:119], v[76:91]
	v_mfma_f32_32x32x16_bf16 v[76:91], v[72:75], v[120:123], v[76:91]
	ds_read_b64_tr_b16 v[36:37], v225 offset:43008
	ds_read_b64_tr_b16 v[38:39], v225 offset:43520
	ds_read_b64_tr_b16 v[72:73], v225 offset:44032
	ds_read_b64_tr_b16 v[74:75], v225 offset:44544
	s_waitcnt lgkmcnt(4)
	ds_read_b128 v[148:151], v210 offset:8704
	ds_read_b128 v[152:155], v210 offset:8736
	ds_read_b128 v[156:159], v210 offset:8768
	ds_read_b128 v[160:163], v210 offset:8800
	s_waitcnt lgkmcnt(3)
	v_mfma_f32_32x32x16_bf16 v[92:107], v[148:151], v[176:179], 0
	ds_read_b128 v[148:151], v210 offset:8832
	v_sub_f32_e32 v2, v250, v251
	v_exp_f32_e32 v2, v2
	s_nop 0
	v_mul_f32_e32 v234, v234, v2
	v_mul_f32_e32 v235, v235, v2
	s_waitcnt lgkmcnt(3)
	v_mfma_f32_32x32x16_bf16 v[92:107], v[152:155], v[180:183], v[92:107]
	ds_read_b128 v[152:155], v210 offset:8864
	v_mul_f32_e32 v236, v236, v2
	v_mul_f32_e32 v237, v237, v2
	v_mul_f32_e32 v238, v238, v2
	v_mul_f32_e32 v239, v239, v2
	v_mul_f32_e32 v240, v240, v2
	s_waitcnt lgkmcnt(3)
	v_mfma_f32_32x32x16_bf16 v[92:107], v[156:159], v[184:187], v[92:107]
	ds_read_b128 v[156:159], v210 offset:8896
	v_mul_f32_e32 v241, v241, v2
	v_mul_f32_e32 v242, v242, v2
	v_mul_f32_e32 v243, v243, v2
	v_mul_f32_e32 v244, v244, v2
	v_mul_f32_e32 v245, v245, v2
	v_mul_f32_e32 v246, v246, v2
	s_waitcnt lgkmcnt(3)
	v_mfma_f32_32x32x16_bf16 v[92:107], v[160:163], v[188:191], v[92:107]
	ds_read_b128 v[160:163], v210 offset:8928
	v_mul_f32_e32 v247, v247, v2
	v_mul_f32_e32 v248, v248, v2
	v_mul_f32_e32 v249, v249, v2
	v_mul_f32_e32 v132, v132, v234
	v_mul_f32_e32 v133, v133, v235
	s_waitcnt lgkmcnt(3)
	v_mfma_f32_32x32x16_bf16 v[92:107], v[148:151], v[192:195], v[92:107]
	v_mul_f32_e32 v134, v134, v236
	v_mul_f32_e32 v135, v135, v237
	v_mul_f32_e32 v136, v136, v238
	v_mul_f32_e32 v137, v137, v239
	v_mul_f32_e32 v138, v138, v240
	s_waitcnt lgkmcnt(2)
	v_mfma_f32_32x32x16_bf16 v[92:107], v[152:155], v[196:199], v[92:107]
	v_mul_f32_e32 v139, v139, v241
	v_mul_f32_e32 v140, v140, v242
	v_mul_f32_e32 v141, v141, v243
	v_mul_f32_e32 v142, v142, v244
	v_mul_f32_e32 v143, v143, v245
	v_mul_f32_e32 v144, v144, v246
	s_waitcnt lgkmcnt(1)
	v_mfma_f32_32x32x16_bf16 v[92:107], v[156:159], v[200:203], v[92:107]
	v_mul_f32_e32 v145, v145, v247
	v_mul_f32_e32 v146, v146, v248
	v_mul_f32_e32 v147, v147, v249
	v_cvt_pk_bf16_f32 v132, v132, v133
	v_cvt_pk_bf16_f32 v133, v134, v135
	s_waitcnt lgkmcnt(0)
	v_mfma_f32_32x32x16_bf16 v[92:107], v[160:163], v[204:207], v[92:107]
	v_cvt_pk_bf16_f32 v134, v136, v137
	v_cvt_pk_bf16_f32 v135, v138, v139
	v_cvt_pk_bf16_f32 v136, v140, v141
	v_cvt_pk_bf16_f32 v137, v142, v143
	v_cvt_pk_bf16_f32 v138, v144, v145
	v_cvt_pk_bf16_f32 v139, v146, v147
	v_mfma_f32_32x32x16_bf16 v[76:91], v[36:39], v[132:135], v[76:91]
	v_mfma_f32_32x32x16_bf16 v[76:91], v[72:75], v[136:139], v[76:91]
	s_branch .Lm_ydone_33
.Lm_yfin1_30:
	ds_write_b128 v168, v[76:79] offset:0
	ds_write_b128 v168, v[80:83] offset:32
	ds_write_b128 v168, v[84:87] offset:64
	ds_write_b128 v168, v[88:91] offset:96
	global_load_dwordx4 v[76:79], v173, s[40:41]
	global_load_dwordx4 v[80:83], v173, s[40:41] offset:1024
	s_waitcnt lgkmcnt(0)
	ds_read_b128 v[92:95], v169 offset:0
	ds_read_b128 v[96:99], v169 offset:16
	ds_read_b128 v[100:103], v169 offset:2304
	ds_read_b128 v[104:107], v169 offset:2320
	s_waitcnt lgkmcnt(0)
	s_waitcnt vmcnt(0)
	v_lshlrev_b32_e32 v108, 16, v76
	v_and_b32_e32 v109, 0xffff0000, v76
	v_fmac_f32_e32 v92, s24, v108
	v_fmac_f32_e32 v93, s24, v109
	v_lshlrev_b32_e32 v108, 16, v77
	v_and_b32_e32 v109, 0xffff0000, v77
	v_fmac_f32_e32 v94, s24, v108
	v_fmac_f32_e32 v95, s24, v109
	v_lshlrev_b32_e32 v108, 16, v78
	v_and_b32_e32 v109, 0xffff0000, v78
	v_fmac_f32_e32 v96, s24, v108
	v_fmac_f32_e32 v97, s24, v109
	v_lshlrev_b32_e32 v108, 16, v79
	v_and_b32_e32 v109, 0xffff0000, v79
	v_fmac_f32_e32 v98, s24, v108
	v_fmac_f32_e32 v99, s24, v109
	v_cvt_pk_bf16_f32 v92, v92, v93
	v_cvt_pk_bf16_f32 v93, v94, v95
	v_cvt_pk_bf16_f32 v94, v96, v97
	v_cvt_pk_bf16_f32 v95, v98, v99
	v_lshlrev_b32_e32 v108, 16, v80
	v_and_b32_e32 v109, 0xffff0000, v80
	v_fmac_f32_e32 v100, s24, v108
	v_fmac_f32_e32 v101, s24, v109
	v_lshlrev_b32_e32 v108, 16, v81
	v_and_b32_e32 v109, 0xffff0000, v81
	v_fmac_f32_e32 v102, s24, v108
	v_fmac_f32_e32 v103, s24, v109
	v_lshlrev_b32_e32 v108, 16, v82
	v_and_b32_e32 v109, 0xffff0000, v82
	v_fmac_f32_e32 v104, s24, v108
	v_fmac_f32_e32 v105, s24, v109
	v_lshlrev_b32_e32 v108, 16, v83
	v_and_b32_e32 v109, 0xffff0000, v83
	v_fmac_f32_e32 v106, s24, v108
	v_fmac_f32_e32 v107, s24, v109
	v_cvt_pk_bf16_f32 v100, v100, v101
	v_cvt_pk_bf16_f32 v101, v102, v103
	v_cvt_pk_bf16_f32 v102, v104, v105
	v_cvt_pk_bf16_f32 v103, v106, v107
	global_store_dwordx4 v170, v[92:95], s[44:45]
	global_store_dwordx4 v171, v[100:103], s[44:45]
	s_cmp_lg_u32 s50, 0
	s_cselect_b32 s4, s49, 0
	s_cselect_b32 s5, s55, 0
	s_cselect_b32 s6, s47, 0
	s_add_u32 s44, s44, s4
	s_addc_u32 s45, s45, s5
	s_add_u32 s40, s40, s6
	s_addc_u32 s41, s41, s5
	s_waitcnt vmcnt(16)
	ds_write_b128 v166, v[4:7] offset:0
	ds_write_b128 v166, v[8:11] offset:272
	ds_write_b128 v166, v[12:15] offset:544
	ds_write_b128 v166, v[16:19] offset:816
	ds_write_b128 v166, v[20:23] offset:1088
	ds_write_b128 v166, v[24:27] offset:1360
	ds_write_b128 v166, v[28:31] offset:1632
	ds_write_b128 v166, v[32:35] offset:1904
	global_load_dwordx4 v[4:7], v164, s[38:39] offset:0
	global_load_dwordx4 v[8:11], v164, s[38:39] offset:512
	global_load_dwordx4 v[12:15], v164, s[38:39] offset:1024
	global_load_dwordx4 v[16:19], v164, s[38:39] offset:1536
	global_load_dwordx4 v[20:23], v164, s[38:39] offset:2048
	global_load_dwordx4 v[24:27], v164, s[38:39] offset:2560
	global_load_dwordx4 v[28:31], v164, s[38:39] offset:3072
	global_load_dwordx4 v[32:35], v164, s[38:39] offset:3584
	s_add_u32 s38, s38, s46
	s_addc_u32 s39, s39, s55
	s_waitcnt lgkmcnt(0)
	ds_read_b64_tr_b16 v[36:37], v225 offset:43008
	ds_read_b64_tr_b16 v[38:39], v225 offset:43520
	ds_read_b64_tr_b16 v[72:73], v225 offset:44032
	ds_read_b64_tr_b16 v[74:75], v225 offset:44544
	ds_read_b128 v[148:151], v210 offset:8704
	ds_read_b128 v[152:155], v210 offset:8736
	ds_read_b128 v[156:159], v210 offset:8768
	ds_read_b128 v[160:163], v210 offset:8800
	s_waitcnt lgkmcnt(3)
	v_mfma_f32_32x32x16_bf16 v[92:107], v[148:151], v[176:179], 0
	ds_read_b128 v[148:151], v210 offset:8832
	v_sub_f32_e32 v234, v250, v234
	v_sub_f32_e32 v235, v250, v235
	v_sub_f32_e32 v236, v250, v236
	v_sub_f32_e32 v237, v250, v237
	v_sub_f32_e32 v238, v250, v238
	v_sub_f32_e32 v239, v250, v239
	v_sub_f32_e32 v240, v250, v240
	v_sub_f32_e32 v241, v250, v241
	v_sub_f32_e32 v242, v250, v242
	s_waitcnt lgkmcnt(3)
	v_mfma_f32_32x32x16_bf16 v[92:107], v[152:155], v[180:183], v[92:107]
	ds_read_b128 v[152:155], v210 offset:8864
	v_sub_f32_e32 v243, v250, v243
	v_sub_f32_e32 v244, v250, v244
	v_sub_f32_e32 v245, v250, v245
	v_sub_f32_e32 v246, v250, v246
	v_sub_f32_e32 v247, v250, v247
	v_sub_f32_e32 v248, v250, v248
	v_sub_f32_e32 v249, v250, v249
	v_exp_f32_e32 v234, v234
	v_exp_f32_e32 v235, v235
	s_waitcnt lgkmcnt(3)
	v_mfma_f32_32x32x16_bf16 v[92:107], v[156:159], v[184:187], v[92:107]
	ds_read_b128 v[156:159], v210 offset:8896
	v_exp_f32_e32 v236, v236
	v_exp_f32_e32 v237, v237
	v_exp_f32_e32 v238, v238
	v_exp_f32_e32 v239, v239
	v_exp_f32_e32 v240, v240
	v_exp_f32_e32 v241, v241
	v_exp_f32_e32 v242, v242
	v_exp_f32_e32 v243, v243
	v_exp_f32_e32 v244, v244
	s_waitcnt lgkmcnt(3)
	v_mfma_f32_32x32x16_bf16 v[92:107], v[160:163], v[188:191], v[92:107]
	ds_read_b128 v[160:163], v210 offset:8928
	v_exp_f32_e32 v245, v245
	v_exp_f32_e32 v246, v246
	v_exp_f32_e32 v247, v247
	v_exp_f32_e32 v248, v248
	v_exp_f32_e32 v249, v249
	v_mul_f32_e32 v116, v116, v234
	v_mul_f32_e32 v117, v117, v235
	v_mul_f32_e32 v118, v118, v236
	v_mul_f32_e32 v119, v119, v237
	s_waitcnt lgkmcnt(3)
	v_mfma_f32_32x32x16_bf16 v[92:107], v[148:151], v[192:195], v[92:107]
	v_mul_f32_e32 v120, v120, v238
	v_mul_f32_e32 v121, v121, v239
	v_mul_f32_e32 v122, v122, v240
	v_mul_f32_e32 v123, v123, v241
	v_mul_f32_e32 v124, v124, v242
	v_mul_f32_e32 v125, v125, v243
	v_mul_f32_e32 v126, v126, v244
	v_mul_f32_e32 v127, v127, v245
	v_mul_f32_e32 v128, v128, v246
	s_waitcnt lgkmcnt(2)
	v_mfma_f32_32x32x16_bf16 v[92:107], v[152:155], v[196:199], v[92:107]
	v_mul_f32_e32 v129, v129, v247
	v_mul_f32_e32 v130, v130, v248
	v_mul_f32_e32 v131, v131, v249
	v_cndmask_b32_e64 v116, 0, v116, s[64:65]
	v_cndmask_b32_e64 v117, 0, v117, s[66:67]
	v_cndmask_b32_e64 v118, 0, v118, s[68:69]
	v_cndmask_b32_e64 v119, 0, v119, s[70:71]
	v_cndmask_b32_e64 v120, 0, v120, s[72:73]
	v_cndmask_b32_e64 v121, 0, v121, s[74:75]
	s_waitcnt lgkmcnt(1)
	v_mfma_f32_32x32x16_bf16 v[92:107], v[156:159], v[200:203], v[92:107]
	v_cndmask_b32_e64 v122, 0, v122, s[76:77]
	v_cndmask_b32_e64 v123, 0, v123, s[78:79]
	v_cndmask_b32_e64 v124, 0, v124, s[80:81]
	v_cndmask_b32_e64 v125, 0, v125, s[82:83]
	v_cndmask_b32_e64 v126, 0, v126, s[84:85]
	v_cndmask_b32_e64 v127, 0, v127, s[86:87]
	v_cndmask_b32_e64 v128, 0, v128, s[88:89]
	v_cndmask_b32_e64 v129, 0, v129, s[90:91]
	v_cndmask_b32_e64 v130, 0, v130, s[92:93]
	s_waitcnt lgkmcnt(0)
	v_mfma_f32_32x32x16_bf16 v[92:107], v[160:163], v[204:207], v[92:107]
	v_cndmask_b32_e64 v131, 0, v131, s[94:95]
	v_cvt_pk_bf16_f32 v116, v116, v117
	v_cvt_pk_bf16_f32 v117, v118, v119
	v_cvt_pk_bf16_f32 v118, v120, v121
	v_cvt_pk_bf16_f32 v119, v122, v123
	v_cvt_pk_bf16_f32 v120, v124, v125
	v_cvt_pk_bf16_f32 v121, v126, v127
	v_cvt_pk_bf16_f32 v122, v128, v129
	v_cvt_pk_bf16_f32 v123, v130, v131
	v_mfma_f32_32x32x16_bf16 v[76:91], v[36:39], v[116:119], 0
	v_mfma_f32_32x32x16_bf16 v[76:91], v[72:75], v[120:123], v[76:91]
	s_waitcnt vmcnt(10)
	v_mul_f32_e32 v132, s62, v146
	v_mul_f32_e32 v133, s62, v147
	v_add_f32_e32 v134, v132, v133
	v_and_b32_e32 v140, 63, v175
	v_lshrrev_b32_e32 v142, 4, v140
	v_add_f32_dpp v134, v134, v134 row_shr:1 row_mask:0xf bank_mask:0xf bound_ctrl:0
	s_nop 1
	v_add_f32_dpp v134, v134, v134 row_shr:2 row_mask:0xf bank_mask:0xf bound_ctrl:0
	s_nop 1
	v_add_f32_dpp v134, v134, v134 row_shr:4 row_mask:0xf bank_mask:0xf bound_ctrl:0
	s_nop 1
	v_add_f32_dpp v134, v134, v134 row_shr:8 row_mask:0xf bank_mask:0xf bound_ctrl:0
	s_nop 1
	v_add_f32_dpp v134, v134, v134 row_bcast:15 row_mask:0xa bank_mask:0xf
	s_nop 1
	v_add_f32_dpp v134, v134, v134 row_bcast:31 row_mask:0xc bank_mask:0xf
	v_lshlrev_b32_e32 v140, 3, v140
	v_lshlrev_b32_e32 v142, 7, v142
	v_readlane_b32 s97, v134, 63
	v_sub_f32_e32 v138, v134, v133
	v_mov_b32_e32 v139, v134
	v_add_u32_e32 v143, 0x1d800, v140
	v_add_u32_e32 v143, s20, v143
	s_cmp_eq_u32 s51, 0
	s_cbranch_scc1 .Lm_scanf_34
	v_sub_f32_e32 v138, s97, v138
	v_sub_f32_e32 v139, s97, v139
	v_fma_f32 v138, v146, s62, v138
	v_fma_f32 v139, v147, s62, v139

.Lm_stepdone_26:
	s_waitcnt lgkmcnt(0)
	s_barrier
	s_mov_b32 s14, s16
	s_mov_b32 s16, s17
	s_add_u32 s17, s17, 1280
	s_cmpk_eq_u32 s17, 5120
	s_cselect_b32 s17, 0, s17
	s_add_u32 s50, s50, 1
	s_cmp_lt_u32 s50, 64
	s_cbranch_scc1 .Lm_loop
	s_cmp_lt_u32 s3, 4
	s_cbranch_scc0 .Lm_noflush_36
	s_nop 7
	s_nop 3
	v_fma_f32 v76, v92, v3, v76
	v_fma_f32 v77, v93, v3, v77
	v_fma_f32 v78, v94, v3, v78
	v_fma_f32 v79, v95, v3, v79
	v_fma_f32 v80, v96, v3, v80
	v_fma_f32 v81, v97, v3, v81
	v_fma_f32 v82, v98, v3, v82
	v_fma_f32 v83, v99, v3, v83
	v_fma_f32 v84, v100, v3, v84
	v_fma_f32 v85, v101, v3, v85
	v_fma_f32 v86, v102, v3, v86
	v_fma_f32 v87, v103, v3, v87
	v_fma_f32 v88, v104, v3, v88
	v_fma_f32 v89, v105, v3, v89
	v_fma_f32 v90, v106, v3, v90
	v_fma_f32 v91, v107, v3, v91
	ds_write_b128 v168, v[76:79] offset:0
	ds_write_b128 v168, v[80:83] offset:32
	ds_write_b128 v168, v[84:87] offset:64
	ds_write_b128 v168, v[88:91] offset:96
	global_load_dwordx4 v[76:79], v173, s[40:41]
	global_load_dwordx4 v[80:83], v173, s[40:41] offset:1024
	s_waitcnt lgkmcnt(0)
	ds_read_b128 v[92:95], v169 offset:0
	ds_read_b128 v[96:99], v169 offset:16
	ds_read_b128 v[100:103], v169 offset:2304
	ds_read_b128 v[104:107], v169 offset:2320
	s_waitcnt vmcnt(0) lgkmcnt(0)
	v_lshlrev_b32_e32 v108, 16, v76
	v_and_b32_e32 v109, 0xffff0000, v76
	v_fmac_f32_e32 v92, s24, v108
	v_fmac_f32_e32 v93, s24, v109
	v_lshlrev_b32_e32 v108, 16, v77
	v_and_b32_e32 v109, 0xffff0000, v77
	v_fmac_f32_e32 v94, s24, v108
	v_fmac_f32_e32 v95, s24, v109
	v_lshlrev_b32_e32 v108, 16, v78
	v_and_b32_e32 v109, 0xffff0000, v78
	v_fmac_f32_e32 v96, s24, v108
	v_fmac_f32_e32 v97, s24, v109
	v_lshlrev_b32_e32 v108, 16, v79
	v_and_b32_e32 v109, 0xffff0000, v79
	v_fmac_f32_e32 v98, s24, v108
	v_fmac_f32_e32 v99, s24, v109
	v_cvt_pk_bf16_f32 v92, v92, v93
	v_cvt_pk_bf16_f32 v93, v94, v95
	v_cvt_pk_bf16_f32 v94, v96, v97
	v_cvt_pk_bf16_f32 v95, v98, v99
	v_lshlrev_b32_e32 v108, 16, v80
	v_and_b32_e32 v109, 0xffff0000, v80
	v_fmac_f32_e32 v100, s24, v108
	v_fmac_f32_e32 v101, s24, v109
	v_lshlrev_b32_e32 v108, 16, v81
	v_and_b32_e32 v109, 0xffff0000, v81
	v_fmac_f32_e32 v102, s24, v108
	v_fmac_f32_e32 v103, s24, v109
	v_lshlrev_b32_e32 v108, 16, v82
	v_and_b32_e32 v109, 0xffff0000, v82
	v_fmac_f32_e32 v104, s24, v108
	v_fmac_f32_e32 v105, s24, v109
	v_lshlrev_b32_e32 v108, 16, v83
	v_and_b32_e32 v109, 0xffff0000, v83
	v_fmac_f32_e32 v106, s24, v108
	v_fmac_f32_e32 v107, s24, v109
	v_cvt_pk_bf16_f32 v100, v100, v101
	v_cvt_pk_bf16_f32 v101, v102, v103
	v_cvt_pk_bf16_f32 v102, v104, v105
	v_cvt_pk_bf16_f32 v103, v106, v107
	global_store_dwordx4 v170, v[92:95], s[44:45]
	global_store_dwordx4 v171, v[100:103], s[44:45]
